# P3 cat stores written through (sc1) so the P3->P4 seam's L2 write-back has little to flush
# speedup vs baseline: 1.0079x; 1.0079x over previous
; __device__ __forceinline__ unsigned cvt_pk(float lo, float hi) { f32x2_t v = {lo, hi}; bf16x2_t b = __builtin_convertvector(v, bf16x2_t); return __builtin_bit_cast(unsigned, b); }
; __device__ __forceinline__ size_t blk_off(int row, int col, int K) { return ((size_t)((row >> 8) * (K >> 6) + (col >> 6)) << 14) + (size_t)(((row & 255) << 6) + (col & 63)); }
; __global__ void __launch_bounds__(NWAVES * 64, 2) fwd(Args a) {
;     ...
;                     lsum = red_sum_16_32(lsum);
;                     const float il = 1.0f / lsum;
; #pragma unroll
;                     for (int pr = 0; pr < 2; ++pr) {
;                         unsigned ex = cvt_pk(oacc[2 * pr][0] * il, oacc[2 * pr][1] * il), ey = cvt_pk(oacc[2 * pr][2] * il, oacc[2 * pr][3] * il);
;                         unsigned ox = cvt_pk(oacc[2 * pr + 1][0] * il, oacc[2 * pr + 1][1] * il), oy = cvt_pk(oacc[2 * pr + 1][2] * il, oacc[2 * pr + 1][3] * il);
;                         asm volatile("s_nop 1\n\tv_permlane16_swap_b32 %0, %1" : "+v"(ex), "+v"(ox)); asm volatile("s_nop 1\n\tv_permlane16_swap_b32 %0, %1" : "+v"(ey), "+v"(oy));
;                         v4u w; w.x = ex; w.y = ey; w.z = ox; w.w = oy;
;                         *(v4u*)(CATg + blk_off(qrow - GROWS * grp, h * 64 + 16 * (2 * pr + (fq & 1)) + 4 * (fq & ~1), D)) = w; }
.LBB0_260:
	v_mov_b32_e32 v2, v114
	s_nop 1
	v_permlane16_swap_b32 v114, v2
	s_add_i32 s28, s58, s87
	v_add_f32_e32 v2, v114, v2
	v_mov_b32_e32 v6, v2
	s_nop 1
	v_permlane32_swap_b32 v2, v6
	s_ashr_i32 s28, s28, 4
	v_add_f32_e32 v2, v2, v6
	v_div_scale_f32 v6, s[56:57], v2, v2, 1.0
	v_rcp_f32_e32 v7, v6
	v_div_scale_f32 v8, vcc, 1.0, v2, 1.0
	s_and_b32 s28, s28, -16
	v_fma_f32 v9, -v6, v7, 1.0
	v_fmac_f32_e32 v7, v9, v7
	v_mul_f32_e32 v9, v8, v7
	v_fma_f32 v10, -v6, v9, v8
	v_fmac_f32_e32 v9, v10, v7
	v_fma_f32 v6, -v6, v9, v8
	v_div_fmas_f32 v6, v6, v7, v9
	v_div_fixup_f32 v2, v6, v2, 1.0
	s_add_i32 s56, s28, s52
	s_ashr_i32 s57, s56, 31
	v_pk_mul_f32 v[6:7], v[2:3], v[102:103] op_sel_hi:[0,1]
	v_pk_mul_f32 v[8:9], v[2:3], v[104:105] op_sel_hi:[0,1]
	s_lshl_b64 s[56:57], s[56:57], 15
	v_cvt_pk_bf16_f32 v6, v6, v7
	v_cvt_pk_bf16_f32 v7, v8, v9
	v_pk_mul_f32 v[8:9], v[2:3], v[110:111] op_sel_hi:[0,1]
	v_pk_mul_f32 v[10:11], v[2:3], v[112:113] op_sel_hi:[0,1]
	s_add_u32 s56, s2, s56
	v_cvt_pk_bf16_f32 v8, v8, v9
	v_cvt_pk_bf16_f32 v9, v10, v11
	v_and_or_b32 v10, v141, s63, v189
	s_addc_u32 s57, s3, s57
	s_nop 1
	v_permlane16_swap_b32 v6, v8
	s_nop 1
	v_permlane16_swap_b32 v7, v9
	v_lshlrev_b32_e32 v12, 1, v10
	global_store_dwordx4 v12, v[6:9], s[56:57] sc1
	v_pk_mul_f32 v[10:11], v[2:3], v[108:109] op_sel_hi:[0,1]
	s_waitcnt vmcnt(1)
	v_mov_b64_e32 v[66:67], v[86:87]
	v_pk_mul_f32 v[6:7], v[2:3], v[98:99] op_sel_hi:[0,1]
	v_pk_mul_f32 v[8:9], v[2:3], v[100:101] op_sel_hi:[0,1]
	v_cvt_pk_bf16_f32 v6, v6, v7
	v_cvt_pk_bf16_f32 v7, v8, v9
	v_pk_mul_f32 v[8:9], v[2:3], v[106:107] op_sel_hi:[0,1]
	v_cvt_pk_bf16_f32 v8, v8, v9
	v_cvt_pk_bf16_f32 v9, v10, v11
	s_nop 1
	v_permlane16_swap_b32 v6, v8
	s_nop 1
	v_permlane16_swap_b32 v7, v9
	global_store_dwordx4 v12, v[6:9], s[56:57] offset:64 sc1
	v_mov_b64_e32 v[70:71], v[82:83]
	v_mov_b32_e32 v81, v97
	v_mov_b64_e32 v[6:7], v[34:35]
	v_mov_b32_e32 v80, v96
	v_mov_b32_e32 v79, v95
	v_mov_b32_e32 v78, v94
	v_mov_b32_e32 v77, v93
	v_mov_b32_e32 v76, v92
	v_mov_b32_e32 v75, v91
	v_mov_b32_e32 v74, v90
	v_mov_b32_e32 v194, v147
	v_mov_b64_e32 v[8:9], v[36:37]
	v_mov_b64_e32 v[10:11], v[38:39]
	v_mov_b64_e32 v[12:13], v[40:41]
	v_mov_b64_e32 v[14:15], v[42:43]
	v_mov_b64_e32 v[16:17], v[44:45]
	v_mov_b64_e32 v[18:19], v[46:47]
	v_mov_b64_e32 v[20:21], v[48:49]
	v_mov_b64_e32 v[22:23], v[50:51]
	v_mov_b64_e32 v[24:25], v[52:53]
	v_mov_b64_e32 v[26:27], v[54:55]
	v_mov_b64_e32 v[28:29], v[56:57]
	v_mov_b64_e32 v[30:31], v[58:59]
	v_mov_b64_e32 v[32:33], v[60:61]
	v_mov_b64_e32 v[68:69], v[88:89]
	v_mov_b64_e32 v[72:73], v[84:85]
	v_mov_b64_e32 v[34:35], v[62:63]
	v_mov_b64_e32 v[36:37], v[64:65]

; __device__ __forceinline__ unsigned pk2(float lo, float hi) { return f2bf(lo) | (f2bf(hi) << 16); }
; __device__ __forceinline__ size_t blk_off(int row, int col, int K) { return ((size_t)((row >> 8) * (K >> 6) + (col >> 6)) << 14) + (size_t)(((row & 255) << 6) + (col & 63)); }
; #define POOL_ADD(sgn, VV) do { S[0] += sgn bflo((VV).x); S[1] += sgn bfhi((VV).x); S[2] += sgn bflo((VV).y); S[3] += sgn bfhi((VV).y); S[4] += sgn bflo((VV).z); S[5] += sgn bfhi((VV).z); S[6] += sgn bflo((VV).w); S[7] += sgn bfhi((VV).w); } while (0)
; template <int HW> __device__ __forceinline__ void pool_group(const bf16* PROJ, bf16* CAT, int pbase, int T, int t0, int ch) {
;     ...
;     for (int i = 0; i < NL; ++i) { const int s = t0 - HW + i; const v4u z = {0u, 0u, 0u, 0u}; x[i] = (s >= 0 && s < T) ? *(const v4u*)(PROJ + (size_t)(pbase + s) * INW + 3 * ATTW + 8 * ch) : z; }
;     float S[8];
; #pragma unroll
;     for (int c = 0; c < 8; ++c) S[c] = 0.f;
;     ...
; #pragma unroll
;     for (int i = 0; i < 2 * HW; ++i) POOL_ADD(+, x[i]);
; #pragma unroll
;     for (int k = 0; k < 4; ++k) {
;         if (k > 0) { POOL_ADD(-, x[k - 1]); POOL_ADD(+, x[k - 1 + 2 * HW]); }
;         const int t = t0 + k; const float ic = 1.0f / (float)(min(t + HW, T) - max(t - HW, 0)); const v4u w = x[HW + k];
;         v4u ow; ow.x = pk2(S[0] * ic - bflo(w.x), S[1] * ic - bfhi(w.x)); ow.y = pk2(S[2] * ic - bflo(w.y), S[3] * ic - bfhi(w.y));
;         ow.z = pk2(S[4] * ic - bflo(w.z), S[5] * ic - bfhi(w.z)); ow.w = pk2(S[6] * ic - bflo(w.w), S[7] * ic - bfhi(w.w));
;         *(v4u*)(CAT + blk_off(pbase + t, ATTW + 8 * ch, D)) = ow;
.LBB0_297:
	s_or_b64 exec, exec, s[72:73]
	s_waitcnt vmcnt(0)
	v_lshlrev_b32_e32 v107, 16, v47
	v_lshlrev_b32_e32 v106, 16, v46
	v_pk_add_f32 v[100:101], v[106:107], 0 op_sel_hi:[1,0]
	v_lshlrev_b32_e32 v103, 16, v43
	v_lshlrev_b32_e32 v102, 16, v42
	v_pk_add_f32 v[104:105], v[100:101], v[102:103]
	v_lshlrev_b32_e32 v101, 16, v63
	v_lshlrev_b32_e32 v100, 16, v62
	v_pk_add_f32 v[104:105], v[104:105], v[100:101]
	v_lshlrev_b32_e32 v111, 16, v59
	v_lshlrev_b32_e32 v110, 16, v58
	v_and_b32_e32 v113, 0xffff0000, v47
	v_and_b32_e32 v112, 0xffff0000, v46
	v_pk_add_f32 v[110:111], v[104:105], v[110:111]
	v_pk_add_f32 v[46:47], v[112:113], 0 op_sel_hi:[1,0]
	v_and_b32_e32 v105, 0xffff0000, v43
	v_and_b32_e32 v104, 0xffff0000, v42
	v_pk_add_f32 v[46:47], v[46:47], v[104:105]
	v_and_b32_e32 v43, 0xffff0000, v63
	v_and_b32_e32 v42, 0xffff0000, v62
	v_pk_add_f32 v[46:47], v[46:47], v[42:43]
	v_and_b32_e32 v59, 0xffff0000, v59
	v_and_b32_e32 v58, 0xffff0000, v58
	v_lshlrev_b32_e32 v117, 16, v49
	v_lshlrev_b32_e32 v116, 16, v48
	v_pk_add_f32 v[114:115], v[46:47], v[58:59]
	v_pk_add_f32 v[46:47], v[116:117], 0 op_sel_hi:[1,0]
	v_lshlrev_b32_e32 v59, 16, v45
	v_lshlrev_b32_e32 v58, 16, v44
	v_pk_add_f32 v[62:63], v[46:47], v[58:59]
	v_lshlrev_b32_e32 v47, 16, v65
	v_lshlrev_b32_e32 v46, 16, v64
	v_pk_add_f32 v[62:63], v[62:63], v[46:47]
	v_lshlrev_b32_e32 v119, 16, v61
	v_lshlrev_b32_e32 v118, 16, v60
	v_and_b32_e32 v121, 0xffff0000, v49
	v_and_b32_e32 v120, 0xffff0000, v48
	v_pk_add_f32 v[118:119], v[62:63], v[118:119]
	v_pk_add_f32 v[48:49], v[120:121], 0 op_sel_hi:[1,0]
	v_and_b32_e32 v63, 0xffff0000, v45
	v_and_b32_e32 v62, 0xffff0000, v44
	v_pk_add_f32 v[48:49], v[48:49], v[62:63]
	v_and_b32_e32 v45, 0xffff0000, v65
	v_and_b32_e32 v44, 0xffff0000, v64
	v_pk_add_f32 v[48:49], v[48:49], v[44:45]
	v_and_b32_e32 v61, 0xffff0000, v61
	v_and_b32_e32 v60, 0xffff0000, v60
	v_pk_add_f32 v[60:61], v[48:49], v[60:61]
	v_min_u32_e32 v48, s28, v109
	v_sub_u32_e64 v49, v196, 4 clamp
	v_sub_u32_e32 v48, v48, v49
	v_cvt_f32_i32_e32 v48, v48
	v_lshlrev_b32_e32 v147, 16, v51
	v_lshlrev_b32_e32 v64, 16, v90
	v_lshlrev_b32_e32 v65, 16, v91
	v_div_scale_f32 v49, s[72:73], v48, v48, 1.0
	v_rcp_f32_e32 v109, v49
	v_and_b32_e32 v90, 0xffff0000, v90
	v_and_b32_e32 v91, 0xffff0000, v91
	v_and_b32_e32 v153, 0xffff0000, v53
	v_fma_f32 v124, -v49, v109, 1.0
	v_fmac_f32_e32 v109, v124, v109
	v_div_scale_f32 v124, vcc, 1.0, v48, 1.0
	v_mul_f32_e32 v125, v124, v109
	v_fma_f32 v146, -v49, v125, v124
	v_fmac_f32_e32 v125, v146, v109
	v_fma_f32 v49, -v49, v125, v124
	v_div_fmas_f32 v49, v49, v109, v125
	v_lshlrev_b32_e32 v146, 16, v50
	v_div_fixup_f32 v124, v49, v48, 1.0
	v_pk_add_f32 v[48:49], v[110:111], v[146:147]
	v_and_b32_e32 v111, 0xffff0000, v51
	v_and_b32_e32 v110, 0xffff0000, v50
	v_pk_add_f32 v[50:51], v[114:115], v[110:111]
	v_pk_add_f32 v[48:49], v[48:49], v[64:65]
	v_lshlrev_b32_e32 v115, 16, v87
	v_lshlrev_b32_e32 v114, 16, v86
	v_pk_add_f32 v[148:149], v[48:49], v[114:115]
	v_lshlrev_b32_e32 v49, 16, v83
	v_lshlrev_b32_e32 v48, 16, v82
	v_pk_add_f32 v[50:51], v[50:51], v[90:91]
	v_and_b32_e32 v87, 0xffff0000, v87
	v_and_b32_e32 v86, 0xffff0000, v86
	v_pk_add_f32 v[148:149], v[148:149], v[48:49]
	v_pk_add_f32 v[150:151], v[50:51], v[86:87]
	v_and_b32_e32 v51, 0xffff0000, v83
	v_and_b32_e32 v50, 0xffff0000, v82
	v_pk_fma_f32 v[82:83], v[124:125], v[148:149], v[146:147] op_sel_hi:[0,1,1] neg_lo:[0,0,1] neg_hi:[0,0,1]
	v_lshlrev_b32_e32 v147, 16, v53
	v_lshlrev_b32_e32 v146, 16, v52
	v_and_b32_e32 v152, 0xffff0000, v52
	v_lshlrev_b32_e32 v122, 16, v92
	v_and_b32_e32 v92, 0xffff0000, v92
	v_lshlrev_b32_e32 v123, 16, v93
	v_and_b32_e32 v93, 0xffff0000, v93
	v_pk_add_f32 v[118:119], v[118:119], v[146:147]
	v_pk_add_f32 v[52:53], v[60:61], v[152:153]
	v_pk_add_f32 v[60:61], v[118:119], v[122:123]
	v_pk_add_f32 v[52:53], v[52:53], v[92:93]
	v_lshlrev_b32_e32 v119, 16, v89
	v_lshlrev_b32_e32 v118, 16, v88
	v_and_b32_e32 v89, 0xffff0000, v89
	v_and_b32_e32 v88, 0xffff0000, v88
	v_pk_add_f32 v[60:61], v[60:61], v[118:119]
	v_pk_add_f32 v[154:155], v[52:53], v[88:89]
	v_lshlrev_b32_e32 v53, 16, v85
	v_lshlrev_b32_e32 v52, 16, v84
	v_pk_add_f32 v[150:151], v[150:151], v[50:51]
	v_pk_add_f32 v[156:157], v[60:61], v[52:53]
	v_and_b32_e32 v61, 0xffff0000, v85
	v_and_b32_e32 v60, 0xffff0000, v84
	v_pk_fma_f32 v[110:111], v[124:125], v[150:151], v[110:111] op_sel_hi:[0,1,1] neg_lo:[0,0,1] neg_hi:[0,0,1]
	v_pk_add_f32 v[154:155], v[154:155], v[60:61]
	v_pk_fma_f32 v[84:85], v[124:125], v[156:157], v[146:147] op_sel_hi:[0,1,1] neg_lo:[0,0,1] neg_hi:[0,0,1]
	v_pk_fma_f32 v[124:125], v[124:125], v[154:155], v[152:153] op_sel_hi:[0,1,1] neg_lo:[0,0,1] neg_hi:[0,0,1]
	v_bfe_u32 v152, v110, 16, 1
	v_bfe_u32 v109, v125, 16, 1
	v_add3_u32 v110, v110, v152, s15
	v_bfe_u32 v152, v85, 16, 1
	v_add3_u32 v109, v125, v109, s15
	v_bfe_u32 v125, v82, 16, 1
	v_add3_u32 v85, v85, v152, s15
	v_add3_u32 v82, v82, v125, s15
	v_lshrrev_b32_e32 v85, 16, v85
	v_min_u32_e32 v108, s28, v108
	v_sub_u32_e64 v2, v2, 4 clamp
	v_bfe_u32 v146, v124, 16, 1
	v_lshrrev_b32_e32 v82, 16, v82
	v_and_or_b32 v85, v109, s90, v85
	v_add_u32_e32 v109, s43, v196
	v_sub_u32_e32 v2, v108, v2
	v_bfe_u32 v147, v111, 16, 1
	v_add3_u32 v124, v124, v146, s15
	v_bfe_u32 v146, v83, 16, 1
	v_and_or_b32 v82, v110, s90, v82
	v_ashrrev_i32_e32 v110, 4, v109
	v_cvt_f32_i32_e32 v125, v2
	v_add3_u32 v111, v111, v147, s15
	v_bfe_u32 v147, v84, 16, 1
	v_add3_u32 v83, v83, v146, s15
	v_and_b32_e32 v110, -16, v110
	v_add3_u32 v84, v84, v147, s15
	v_lshrrev_b32_e32 v83, 16, v83
	v_add_u32_e32 v110, v110, v173
	v_lshrrev_b32_e32 v84, 16, v84
; __device__ __forceinline__ unsigned pk2(float lo, float hi) { return f2bf(lo) | (f2bf(hi) << 16); }
; __device__ __forceinline__ size_t blk_off(int row, int col, int K) { return ((size_t)((row >> 8) * (K >> 6) + (col >> 6)) << 14) + (size_t)(((row & 255) << 6) + (col & 63)); }
; #define POOL_ADD(sgn, VV) do { S[0] += sgn bflo((VV).x); S[1] += sgn bfhi((VV).x); S[2] += sgn bflo((VV).y); S[3] += sgn bfhi((VV).y); S[4] += sgn bflo((VV).z); S[5] += sgn bfhi((VV).z); S[6] += sgn bflo((VV).w); S[7] += sgn bfhi((VV).w); } while (0)
; template <int HW> __device__ __forceinline__ void pool_group(const bf16* PROJ, bf16* CAT, int pbase, int T, int t0, int ch) {
;     ...
;     for (int i = 0; i < NL; ++i) { const int s = t0 - HW + i; const v4u z = {0u, 0u, 0u, 0u}; x[i] = (s >= 0 && s < T) ? *(const v4u*)(PROJ + (size_t)(pbase + s) * INW + 3 * ATTW + 8 * ch) : z; }
;     float S[8];
; #pragma unroll
;     for (int c = 0; c < 8; ++c) S[c] = 0.f;
;     ...
; #pragma unroll
;     for (int i = 0; i < 2 * HW; ++i) POOL_ADD(+, x[i]);
; #pragma unroll
;     for (int k = 0; k < 4; ++k) {
;         if (k > 0) { POOL_ADD(-, x[k - 1]); POOL_ADD(+, x[k - 1 + 2 * HW]); }
;         const int t = t0 + k; const float ic = 1.0f / (float)(min(t + HW, T) - max(t - HW, 0)); const v4u w = x[HW + k];
;         v4u ow; ow.x = pk2(S[0] * ic - bflo(w.x), S[1] * ic - bfhi(w.x)); ow.y = pk2(S[2] * ic - bflo(w.y), S[3] * ic - bfhi(w.y));
;         ow.z = pk2(S[4] * ic - bflo(w.z), S[5] * ic - bfhi(w.z)); ow.w = pk2(S[6] * ic - bflo(w.w), S[7] * ic - bfhi(w.w));
;         *(v4u*)(CAT + blk_off(pbase + t, ATTW + 8 * ch, D)) = ow;
	v_and_or_b32 v83, v111, s90, v83
	v_ashrrev_i32_e32 v111, 31, v110
	v_lshlrev_b32_e32 v109, 6, v109
	v_and_or_b32 v84, v124, s90, v84
	v_and_or_b32 v124, v109, s63, v174
	v_lshlrev_b64 v[108:109], 15, v[110:111]
	v_div_scale_f32 v110, s[72:73], v125, v125, 1.0
	v_rcp_f32_e32 v111, v110
	v_lshl_add_u64 v[108:109], s[2:3], 0, v[108:109]
	v_lshlrev_b32_e32 v2, 1, v124
	v_lshl_add_u64 v[108:109], v[108:109], 0, v[2:3]
	v_fma_f32 v2, -v110, v111, 1.0
	v_fmac_f32_e32 v111, v2, v111
	v_div_scale_f32 v2, vcc, 1.0, v125, 1.0
	global_store_dwordx4 v[108:109], v[82:85], off sc1
	s_nop 1
	v_mul_f32_e32 v82, v2, v111
	v_fma_f32 v83, -v110, v82, v2
	v_fmac_f32_e32 v82, v83, v111
	v_fma_f32 v2, -v110, v82, v2
	v_div_fmas_f32 v2, v2, v111, v82
	v_pk_add_f32 v[82:83], v[148:149], v[106:107] neg_lo:[0,1] neg_hi:[0,1]
	v_lshlrev_b32_e32 v85, 16, v55
	v_lshlrev_b32_e32 v84, 16, v54
	v_pk_add_f32 v[82:83], v[82:83], v[84:85]
	v_pk_add_f32 v[84:85], v[150:151], v[112:113] neg_lo:[0,1] neg_hi:[0,1]
	v_and_b32_e32 v55, 0xffff0000, v55
	v_and_b32_e32 v54, 0xffff0000, v54
	v_div_fixup_f32 v2, v2, v125, 1.0
	v_pk_add_f32 v[84:85], v[84:85], v[54:55]
	v_pk_fma_f32 v[54:55], v[2:3], v[82:83], v[64:65] op_sel_hi:[0,1,1] neg_lo:[0,0,1] neg_hi:[0,0,1]
	v_pk_fma_f32 v[64:65], v[2:3], v[84:85], v[90:91] op_sel_hi:[0,1,1] neg_lo:[0,0,1] neg_hi:[0,0,1]
	v_pk_add_f32 v[90:91], v[156:157], v[116:117] neg_lo:[0,1] neg_hi:[0,1]
	v_lshlrev_b32_e32 v107, 16, v57
	v_lshlrev_b32_e32 v106, 16, v56
	v_pk_add_f32 v[90:91], v[90:91], v[106:107]
	v_pk_add_f32 v[106:107], v[154:155], v[120:121] neg_lo:[0,1] neg_hi:[0,1]
	v_and_b32_e32 v57, 0xffff0000, v57
	v_and_b32_e32 v56, 0xffff0000, v56
	v_pk_add_f32 v[106:107], v[106:107], v[56:57]
	v_pk_fma_f32 v[56:57], v[2:3], v[90:91], v[122:123] op_sel_hi:[0,1,1] neg_lo:[0,0,1] neg_hi:[0,0,1]
	v_bfe_u32 v109, v65, 16, 1
	v_pk_fma_f32 v[92:93], v[2:3], v[106:107], v[92:93] op_sel_hi:[0,1,1] neg_lo:[0,0,1] neg_hi:[0,0,1]
	v_add3_u32 v65, v65, v109, s15
	v_bfe_u32 v109, v56, 16, 1
	v_bfe_u32 v2, v93, 16, 1
	v_bfe_u32 v108, v92, 16, 1
	v_add3_u32 v56, v56, v109, s15
	v_add3_u32 v92, v92, v108, s15
	v_add3_u32 v2, v93, v2, s15
	v_bfe_u32 v93, v54, 16, 1
	v_lshrrev_b32_e32 v56, 16, v56
	v_add3_u32 v54, v54, v93, s15
	v_and_or_b32 v56, v92, s90, v56
	v_min_u32_e32 v92, s28, v95
	v_sub_u32_e64 v93, v99, 4 clamp
	v_bfe_u32 v110, v64, 16, 1
	v_sub_u32_e32 v92, v92, v93
	v_add3_u32 v64, v64, v110, s15
	v_bfe_u32 v110, v57, 16, 1
	v_cvt_f32_i32_e32 v92, v92
	v_add3_u32 v57, v57, v110, s15
	v_lshrrev_b32_e32 v57, 16, v57
	v_bfe_u32 v108, v55, 16, 1
	v_and_or_b32 v57, v2, s90, v57
	v_ashrrev_i32_e32 v2, 4, v98
	v_add3_u32 v55, v55, v108, s15
	v_lshrrev_b32_e32 v54, 16, v54
	v_and_b32_e32 v2, -16, v2
	v_div_scale_f32 v93, s[72:73], v92, v92, 1.0
	v_lshrrev_b32_e32 v55, 16, v55
	v_and_or_b32 v54, v64, s90, v54
	v_add_u32_e32 v64, v2, v173
	v_rcp_f32_e32 v95, v93
	v_and_or_b32 v55, v65, s90, v55
	v_ashrrev_i32_e32 v65, 31, v64
	v_lshlrev_b32_e32 v2, 6, v98
	v_and_or_b32 v2, v2, s63, v174
	v_lshlrev_b64 v[64:65], 15, v[64:65]
	v_lshl_add_u64 v[64:65], s[2:3], 0, v[64:65]
	v_lshlrev_b32_e32 v2, 1, v2
	v_lshl_add_u64 v[64:65], v[64:65], 0, v[2:3]
	v_fma_f32 v2, -v93, v95, 1.0
	v_fmac_f32_e32 v95, v2, v95
	v_div_scale_f32 v2, vcc, 1.0, v92, 1.0
	global_store_dwordx4 v[64:65], v[54:57], off sc1
	v_pk_add_f32 v[58:59], v[90:91], v[58:59] neg_lo:[0,1] neg_hi:[0,1]
	v_pk_add_f32 v[62:63], v[106:107], v[62:63] neg_lo:[0,1] neg_hi:[0,1]
	v_mul_f32_e32 v54, v2, v95
	v_fma_f32 v55, -v93, v54, v2
	v_fmac_f32_e32 v54, v55, v95
	v_fma_f32 v2, -v93, v54, v2
	v_div_fmas_f32 v2, v2, v95, v54
	v_pk_add_f32 v[54:55], v[82:83], v[102:103] neg_lo:[0,1] neg_hi:[0,1]
	v_lshlrev_b32_e32 v57, 16, v39
	v_lshlrev_b32_e32 v56, 16, v38
	v_pk_add_f32 v[54:55], v[54:55], v[56:57]
	v_pk_add_f32 v[56:57], v[84:85], v[104:105] neg_lo:[0,1] neg_hi:[0,1]
	v_and_b32_e32 v39, 0xffff0000, v39
	v_and_b32_e32 v38, 0xffff0000, v38
	v_div_fixup_f32 v2, v2, v92, 1.0
	v_pk_add_f32 v[56:57], v[56:57], v[38:39]
	v_lshlrev_b32_e32 v83, 16, v41
	v_lshlrev_b32_e32 v82, 16, v40
	v_pk_fma_f32 v[64:65], v[2:3], v[56:57], v[86:87] op_sel_hi:[0,1,1] neg_lo:[0,0,1] neg_hi:[0,0,1]
	v_pk_add_f32 v[58:59], v[58:59], v[82:83]
	v_and_b32_e32 v41, 0xffff0000, v41
; __device__ __forceinline__ unsigned pk2(float lo, float hi) { return f2bf(lo) | (f2bf(hi) << 16); }
; __device__ __forceinline__ size_t blk_off(int row, int col, int K) { return ((size_t)((row >> 8) * (K >> 6) + (col >> 6)) << 14) + (size_t)(((row & 255) << 6) + (col & 63)); }
; #define POOL_ADD(sgn, VV) do { S[0] += sgn bflo((VV).x); S[1] += sgn bfhi((VV).x); S[2] += sgn bflo((VV).y); S[3] += sgn bfhi((VV).y); S[4] += sgn bflo((VV).z); S[5] += sgn bfhi((VV).z); S[6] += sgn bflo((VV).w); S[7] += sgn bfhi((VV).w); } while (0)
; template <int HW> __device__ __forceinline__ void pool_group(const bf16* PROJ, bf16* CAT, int pbase, int T, int t0, int ch) {
;     ...
;     for (int i = 0; i < NL; ++i) { const int s = t0 - HW + i; const v4u z = {0u, 0u, 0u, 0u}; x[i] = (s >= 0 && s < T) ? *(const v4u*)(PROJ + (size_t)(pbase + s) * INW + 3 * ATTW + 8 * ch) : z; }
;     float S[8];
; #pragma unroll
;     for (int c = 0; c < 8; ++c) S[c] = 0.f;
;     ...
; #pragma unroll
;     for (int i = 0; i < 2 * HW; ++i) POOL_ADD(+, x[i]);
; #pragma unroll
;     for (int k = 0; k < 4; ++k) {
;         if (k > 0) { POOL_ADD(-, x[k - 1]); POOL_ADD(+, x[k - 1 + 2 * HW]); }
;         const int t = t0 + k; const float ic = 1.0f / (float)(min(t + HW, T) - max(t - HW, 0)); const v4u w = x[HW + k];
;         v4u ow; ow.x = pk2(S[0] * ic - bflo(w.x), S[1] * ic - bfhi(w.x)); ow.y = pk2(S[2] * ic - bflo(w.y), S[3] * ic - bfhi(w.y));
;         ow.z = pk2(S[4] * ic - bflo(w.z), S[5] * ic - bfhi(w.z)); ow.w = pk2(S[6] * ic - bflo(w.w), S[7] * ic - bfhi(w.w));
;         *(v4u*)(CAT + blk_off(pbase + t, ATTW + 8 * ch, D)) = ow;
	v_and_b32_e32 v40, 0xffff0000, v40
	v_pk_add_f32 v[62:63], v[62:63], v[40:41]
	v_pk_fma_f32 v[40:41], v[2:3], v[58:59], v[118:119] op_sel_hi:[0,1,1] neg_lo:[0,0,1] neg_hi:[0,0,1]
	v_bfe_u32 v85, v65, 16, 1
	v_pk_fma_f32 v[82:83], v[2:3], v[62:63], v[88:89] op_sel_hi:[0,1,1] neg_lo:[0,0,1] neg_hi:[0,0,1]
	v_add3_u32 v65, v65, v85, s15
	v_bfe_u32 v85, v40, 16, 1
	v_bfe_u32 v84, v82, 16, 1
	v_add3_u32 v40, v40, v85, s15
	v_pk_fma_f32 v[38:39], v[2:3], v[54:55], v[114:115] op_sel_hi:[0,1,1] neg_lo:[0,0,1] neg_hi:[0,0,1]
	v_bfe_u32 v2, v83, 16, 1
	v_add3_u32 v82, v82, v84, s15
	v_lshrrev_b32_e32 v40, 16, v40
	v_add3_u32 v2, v83, v2, s15
	v_bfe_u32 v83, v38, 16, 1
	v_and_or_b32 v40, v82, s90, v40
	v_add_u32_e32 v82, 7, v196
	v_add3_u32 v38, v38, v83, s15
	v_min_u32_e32 v82, s28, v82
	v_sub_u32_e64 v83, v97, 4 clamp
	v_bfe_u32 v86, v64, 16, 1
	v_sub_u32_e32 v82, v82, v83
	v_add3_u32 v64, v64, v86, s15
	v_bfe_u32 v86, v41, 16, 1
	v_cvt_f32_i32_e32 v82, v82
	v_add3_u32 v41, v41, v86, s15
	v_lshrrev_b32_e32 v41, 16, v41
	v_bfe_u32 v84, v39, 16, 1
	v_and_or_b32 v41, v2, s90, v41
	v_ashrrev_i32_e32 v2, 4, v96
	v_add3_u32 v39, v39, v84, s15
	v_lshrrev_b32_e32 v38, 16, v38
	v_and_b32_e32 v2, -16, v2
	v_div_scale_f32 v83, s[72:73], v82, v82, 1.0
	v_lshrrev_b32_e32 v39, 16, v39
	v_and_or_b32 v38, v64, s90, v38
	v_add_u32_e32 v64, v2, v173
	v_rcp_f32_e32 v84, v83
	v_and_or_b32 v39, v65, s90, v39
	v_ashrrev_i32_e32 v65, 31, v64
	v_lshlrev_b32_e32 v2, 6, v96
	v_and_or_b32 v2, v2, s63, v174
	v_lshlrev_b64 v[64:65], 15, v[64:65]
	v_lshl_add_u64 v[64:65], s[2:3], 0, v[64:65]
	v_lshlrev_b32_e32 v2, 1, v2
	v_lshl_add_u64 v[64:65], v[64:65], 0, v[2:3]
	v_fma_f32 v2, -v83, v84, 1.0
	v_fmac_f32_e32 v84, v2, v84
	v_div_scale_f32 v2, vcc, 1.0, v82, 1.0
	global_store_dwordx4 v[64:65], v[38:41], off sc1
	s_mov_b64 s[72:73], 0
	s_nop 0
	v_mul_f32_e32 v38, v2, v84
	v_fma_f32 v39, -v83, v38, v2
	v_fmac_f32_e32 v38, v39, v84
	v_fma_f32 v2, -v83, v38, v2
	v_div_fmas_f32 v2, v2, v84, v38
	v_pk_add_f32 v[38:39], v[54:55], v[100:101] neg_lo:[0,1] neg_hi:[0,1]
	v_lshlrev_b32_e32 v41, 16, v35
	v_lshlrev_b32_e32 v40, 16, v34
	v_pk_add_f32 v[38:39], v[38:39], v[40:41]
	v_pk_add_f32 v[40:41], v[56:57], v[42:43] neg_lo:[0,1] neg_hi:[0,1]
	v_and_b32_e32 v35, 0xffff0000, v35
	v_and_b32_e32 v34, 0xffff0000, v34
	v_pk_add_f32 v[34:35], v[40:41], v[34:35]
	v_pk_add_f32 v[40:41], v[58:59], v[46:47] neg_lo:[0,1] neg_hi:[0,1]
	v_lshlrev_b32_e32 v43, 16, v37
	v_lshlrev_b32_e32 v42, 16, v36
	v_pk_add_f32 v[40:41], v[40:41], v[42:43]
	v_pk_add_f32 v[42:43], v[62:63], v[44:45] neg_lo:[0,1] neg_hi:[0,1]
	v_and_b32_e32 v37, 0xffff0000, v37
	v_and_b32_e32 v36, 0xffff0000, v36
	v_div_fixup_f32 v2, v2, v82, 1.0
	v_pk_add_f32 v[36:37], v[42:43], v[36:37]
	v_pk_fma_f32 v[34:35], v[2:3], v[34:35], v[50:51] op_sel_hi:[0,1,1] neg_lo:[0,0,1] neg_hi:[0,0,1]
	v_pk_fma_f32 v[36:37], v[2:3], v[36:37], v[60:61] op_sel_hi:[0,1,1] neg_lo:[0,0,1] neg_hi:[0,0,1]
	v_pk_fma_f32 v[38:39], v[2:3], v[38:39], v[48:49] op_sel_hi:[0,1,1] neg_lo:[0,0,1] neg_hi:[0,0,1]
	v_pk_fma_f32 v[40:41], v[2:3], v[40:41], v[52:53] op_sel_hi:[0,1,1] neg_lo:[0,0,1] neg_hi:[0,0,1]
	v_bfe_u32 v2, v37, 16, 1
	v_bfe_u32 v44, v34, 16, 1
	v_add3_u32 v34, v34, v44, s15
	v_add3_u32 v2, v37, v2, s15
	v_bfe_u32 v37, v38, 16, 1
	v_bfe_u32 v44, v41, 16, 1
	v_add3_u32 v41, v41, v44, s15
	v_add3_u32 v37, v38, v37, s15
	v_bfe_u32 v42, v36, 16, 1
	v_lshrrev_b32_e32 v38, 16, v37
	v_lshrrev_b32_e32 v37, 16, v41
	v_add3_u32 v36, v36, v42, s15
	v_bfe_u32 v42, v39, 16, 1
	v_and_or_b32 v37, v2, s90, v37
	v_ashrrev_i32_e32 v2, 4, v94
	v_bfe_u32 v43, v35, 16, 1
	v_add3_u32 v39, v39, v42, s15
	v_and_b32_e32 v2, -16, v2
	v_add3_u32 v35, v35, v43, s15
	v_lshrrev_b32_e32 v39, 16, v39
	v_and_or_b32 v34, v34, s90, v38
	v_add_u32_e32 v38, v2, v173
	v_bfe_u32 v43, v40, 16, 1
	v_and_or_b32 v35, v35, s90, v39
	v_ashrrev_i32_e32 v39, 31, v38
	v_lshlrev_b32_e32 v2, 6, v94
	v_add3_u32 v40, v40, v43, s15
	v_and_or_b32 v2, v2, s63, v174
	v_lshlrev_b64 v[38:39], 15, v[38:39]
	v_lshrrev_b32_e32 v40, 16, v40
	v_lshl_add_u64 v[38:39], s[2:3], 0, v[38:39]
	v_lshlrev_b32_e32 v2, 1, v2
	v_and_or_b32 v36, v36, s90, v40
	v_lshl_add_u64 v[38:39], v[38:39], 0, v[2:3]
	global_store_dwordx4 v[38:39], v[34:37], off sc1

; __device__ __forceinline__ unsigned pk2(float lo, float hi) { return f2bf(lo) | (f2bf(hi) << 16); }
; __device__ __forceinline__ size_t blk_off(int row, int col, int K) { return ((size_t)((row >> 8) * (K >> 6) + (col >> 6)) << 14) + (size_t)(((row & 255) << 6) + (col & 63)); }
; #define POOL_ADD(sgn, VV) do { S[0] += sgn bflo((VV).x); S[1] += sgn bfhi((VV).x); S[2] += sgn bflo((VV).y); S[3] += sgn bfhi((VV).y); S[4] += sgn bflo((VV).z); S[5] += sgn bfhi((VV).z); S[6] += sgn bflo((VV).w); S[7] += sgn bfhi((VV).w); } while (0)
; template <int HW> __device__ __forceinline__ void pool_group(const bf16* PROJ, bf16* CAT, int pbase, int T, int t0, int ch) {
;     ...
;     for (int i = 0; i < NL; ++i) { const int s = t0 - HW + i; const v4u z = {0u, 0u, 0u, 0u}; x[i] = (s >= 0 && s < T) ? *(const v4u*)(PROJ + (size_t)(pbase + s) * INW + 3 * ATTW + 8 * ch) : z; }
;     float S[8];
; #pragma unroll
;     for (int c = 0; c < 8; ++c) S[c] = 0.f;
;     ...
; #pragma unroll
;     for (int i = 0; i < 2 * HW; ++i) POOL_ADD(+, x[i]);
; #pragma unroll
;     for (int k = 0; k < 4; ++k) {
;         if (k > 0) { POOL_ADD(-, x[k - 1]); POOL_ADD(+, x[k - 1 + 2 * HW]); }
;         const int t = t0 + k; const float ic = 1.0f / (float)(min(t + HW, T) - max(t - HW, 0)); const v4u w = x[HW + k];
;         v4u ow; ow.x = pk2(S[0] * ic - bflo(w.x), S[1] * ic - bfhi(w.x)); ow.y = pk2(S[2] * ic - bflo(w.y), S[3] * ic - bfhi(w.y));
;         ow.z = pk2(S[4] * ic - bflo(w.z), S[5] * ic - bfhi(w.z)); ow.w = pk2(S[6] * ic - bflo(w.w), S[7] * ic - bfhi(w.w));
;         *(v4u*)(CAT + blk_off(pbase + t, ATTW + 8 * ch, D)) = ow;
.LBB0_314:
	s_or_b64 exec, exec, s[74:75]
	s_waitcnt vmcnt(0)
	v_lshlrev_b32_e32 v90, 16, v58
	v_and_b32_e32 v92, 0xffff0000, v58
	v_lshlrev_b32_e32 v94, 16, v60
	v_and_b32_e32 v96, 0xffff0000, v60
	v_lshlrev_b32_e32 v98, 16, v50
	v_and_b32_e32 v60, 0xffff0000, v50
	v_min_u32_e32 v50, s28, v83
	v_sub_u32_e64 v58, v196, 2 clamp
	v_sub_u32_e32 v50, v50, v58
	v_cvt_f32_i32_e32 v50, v50
	v_lshlrev_b32_e32 v95, 16, v61
	v_and_b32_e32 v97, 0xffff0000, v61
	v_lshlrev_b32_e32 v99, 16, v51
	v_and_b32_e32 v61, 0xffff0000, v51
	v_div_scale_f32 v51, s[74:75], v50, v50, 1.0
	v_rcp_f32_e32 v86, v51
	v_lshlrev_b32_e32 v84, 16, v52
	v_and_b32_e32 v58, 0xffff0000, v52
	v_lshlrev_b32_e32 v91, 16, v59
	v_fma_f32 v52, -v51, v86, 1.0
	v_fmac_f32_e32 v86, v52, v86
	v_div_scale_f32 v52, vcc, 1.0, v50, 1.0
	v_and_b32_e32 v93, 0xffff0000, v59
	v_lshlrev_b32_e32 v85, 16, v53
	v_and_b32_e32 v59, 0xffff0000, v53
	v_mul_f32_e32 v53, v52, v86
	v_fma_f32 v87, -v51, v53, v52
	v_fmac_f32_e32 v53, v87, v86
	v_fma_f32 v51, -v51, v53, v52
	v_div_fmas_f32 v51, v51, v86, v53
	v_div_fixup_f32 v86, v51, v50, 1.0
	v_pk_add_f32 v[50:51], v[90:91], 0 op_sel_hi:[1,0]
	v_pk_add_f32 v[52:53], v[92:93], 0 op_sel_hi:[1,0]
	v_pk_add_f32 v[50:51], v[50:51], v[98:99]
	v_pk_add_f32 v[88:89], v[52:53], v[60:61]
	v_lshlrev_b32_e32 v53, 16, v55
	v_lshlrev_b32_e32 v52, 16, v54
	v_pk_add_f32 v[100:101], v[50:51], v[52:53]
	v_and_b32_e32 v51, 0xffff0000, v55
	v_and_b32_e32 v50, 0xffff0000, v54
	v_pk_add_f32 v[54:55], v[88:89], v[50:51]
	v_and_b32_e32 v105, 0xffff0000, v47
	v_and_b32_e32 v104, 0xffff0000, v46
	v_lshlrev_b32_e32 v103, 16, v47
	v_lshlrev_b32_e32 v102, 16, v46
	v_pk_add_f32 v[106:107], v[54:55], v[104:105]
	v_pk_add_f32 v[46:47], v[94:95], 0 op_sel_hi:[1,0]
	v_pk_add_f32 v[54:55], v[96:97], 0 op_sel_hi:[1,0]
	v_pk_add_f32 v[46:47], v[46:47], v[84:85]
	v_pk_add_f32 v[110:111], v[54:55], v[58:59]
	v_lshlrev_b32_e32 v55, 16, v57
	v_lshlrev_b32_e32 v54, 16, v56
	v_pk_add_f32 v[112:113], v[46:47], v[54:55]
	v_and_b32_e32 v47, 0xffff0000, v57
	v_and_b32_e32 v46, 0xffff0000, v56
	v_pk_add_f32 v[56:57], v[110:111], v[46:47]
	v_lshlrev_b32_e32 v111, 16, v49
	v_lshlrev_b32_e32 v110, 16, v48
	v_and_b32_e32 v49, 0xffff0000, v49
	v_and_b32_e32 v48, 0xffff0000, v48
	v_pk_add_f32 v[100:101], v[100:101], v[102:103]
	v_pk_add_f32 v[112:113], v[112:113], v[110:111]
	v_pk_add_f32 v[56:57], v[56:57], v[48:49]
	v_pk_fma_f32 v[88:89], v[86:87], v[100:101], v[52:53] op_sel_hi:[0,1,1] neg_lo:[0,0,1] neg_hi:[0,0,1]
	v_pk_fma_f32 v[108:109], v[86:87], v[106:107], v[50:51] op_sel_hi:[0,1,1] neg_lo:[0,0,1] neg_hi:[0,0,1]
	v_pk_fma_f32 v[114:115], v[86:87], v[112:113], v[54:55] op_sel_hi:[0,1,1] neg_lo:[0,0,1] neg_hi:[0,0,1]
	v_pk_fma_f32 v[86:87], v[86:87], v[56:57], v[46:47] op_sel_hi:[0,1,1] neg_lo:[0,0,1] neg_hi:[0,0,1]
	v_bfe_u32 v117, v86, 16, 1
	v_bfe_u32 v119, v108, 16, 1
	v_add3_u32 v108, v108, v119, s15
	v_add3_u32 v86, v86, v117, s15
	v_bfe_u32 v117, v89, 16, 1
	v_bfe_u32 v119, v115, 16, 1
	v_add3_u32 v115, v115, v119, s15
	v_add3_u32 v89, v89, v117, s15
	v_lshrrev_b32_e32 v117, 16, v89
	v_lshrrev_b32_e32 v89, 16, v115
	v_min_u32_e32 v115, s28, v65
	v_sub_u32_e64 v2, v2, 2 clamp
	v_bfe_u32 v116, v87, 16, 1
	v_bfe_u32 v118, v109, 16, 1
	v_sub_u32_e32 v2, v115, v2
	v_add3_u32 v109, v109, v118, s15
	v_add3_u32 v87, v87, v116, s15
	v_bfe_u32 v116, v88, 16, 1
	v_bfe_u32 v118, v114, 16, 1
	v_cvt_f32_i32_e32 v115, v2
	v_add3_u32 v114, v114, v118, s15
	v_add3_u32 v88, v88, v116, s15
	v_lshrrev_b32_e32 v116, 16, v88
	v_lshrrev_b32_e32 v88, 16, v114
	v_add_u32_e32 v114, s43, v196
	v_and_or_b32 v88, v86, s90, v88
	v_and_or_b32 v86, v108, s90, v116
	v_ashrrev_i32_e32 v108, 4, v114
	v_and_b32_e32 v108, -16, v108
	v_div_scale_f32 v116, s[74:75], v115, v115, 1.0
	v_and_or_b32 v89, v87, s90, v89
	v_and_or_b32 v87, v109, s90, v117
	v_add_u32_e32 v108, v108, v173
	v_rcp_f32_e32 v117, v116
	v_ashrrev_i32_e32 v109, 31, v108
	v_lshlrev_b32_e32 v114, 6, v114
	v_and_or_b32 v114, v114, s63, v174
	v_lshlrev_b64 v[108:109], 15, v[108:109]
	v_lshl_add_u64 v[108:109], s[2:3], 0, v[108:109]
	v_lshlrev_b32_e32 v2, 1, v114
	v_lshl_add_u64 v[108:109], v[108:109], 0, v[2:3]
	v_fma_f32 v2, -v116, v117, 1.0
	v_fmac_f32_e32 v117, v2, v117
	v_div_scale_f32 v2, vcc, 1.0, v115, 1.0
	global_store_dwordx4 v[108:109], v[86:89], off sc1
	v_pk_add_f32 v[94:95], v[112:113], v[94:95] neg_lo:[0,1] neg_hi:[0,1]
	v_pk_add_f32 v[56:57], v[56:57], v[96:97] neg_lo:[0,1] neg_hi:[0,1]
	v_mul_f32_e32 v86, v2, v117
	v_fma_f32 v87, -v116, v86, v2
	v_fmac_f32_e32 v86, v87, v117
	v_fma_f32 v2, -v116, v86, v2
	v_div_fmas_f32 v2, v2, v117, v86
	v_pk_add_f32 v[86:87], v[100:101], v[90:91] neg_lo:[0,1] neg_hi:[0,1]
	v_lshlrev_b32_e32 v89, 16, v43
	v_lshlrev_b32_e32 v88, 16, v42
	v_div_fixup_f32 v2, v2, v115, 1.0
	v_pk_add_f32 v[86:87], v[86:87], v[88:89]
	v_pk_add_f32 v[90:91], v[106:107], v[92:93] neg_lo:[0,1] neg_hi:[0,1]
	v_and_b32_e32 v93, 0xffff0000, v43
	v_and_b32_e32 v92, 0xffff0000, v42
	v_pk_add_f32 v[90:91], v[90:91], v[92:93]
	v_pk_fma_f32 v[42:43], v[2:3], v[86:87], v[102:103] op_sel_hi:[0,1,1] neg_lo:[0,0,1] neg_hi:[0,0,1]
	v_lshlrev_b32_e32 v103, 16, v45
	v_lshlrev_b32_e32 v102, 16, v44
	v_pk_fma_f32 v[100:101], v[2:3], v[90:91], v[104:105] op_sel_hi:[0,1,1] neg_lo:[0,0,1] neg_hi:[0,0,1]
	v_pk_add_f32 v[94:95], v[94:95], v[102:103]
	v_and_b32_e32 v97, 0xffff0000, v45
	v_and_b32_e32 v96, 0xffff0000, v44
	v_min_u32_e32 v63, s28, v63
	v_pk_add_f32 v[56:57], v[56:57], v[96:97]
	v_pk_fma_f32 v[44:45], v[2:3], v[94:95], v[110:111] op_sel_hi:[0,1,1] neg_lo:[0,0,1] neg_hi:[0,0,1]
	v_bfe_u32 v106, v100, 16, 1
	v_sub_u32_e32 v63, v63, v83
; __device__ __forceinline__ unsigned pk2(float lo, float hi) { return f2bf(lo) | (f2bf(hi) << 16); }
; __device__ __forceinline__ size_t blk_off(int row, int col, int K) { return ((size_t)((row >> 8) * (K >> 6) + (col >> 6)) << 14) + (size_t)(((row & 255) << 6) + (col & 63)); }
; #define POOL_ADD(sgn, VV) do { S[0] += sgn bflo((VV).x); S[1] += sgn bfhi((VV).x); S[2] += sgn bflo((VV).y); S[3] += sgn bfhi((VV).y); S[4] += sgn bflo((VV).z); S[5] += sgn bfhi((VV).z); S[6] += sgn bflo((VV).w); S[7] += sgn bfhi((VV).w); } while (0)
; template <int HW> __device__ __forceinline__ void pool_group(const bf16* PROJ, bf16* CAT, int pbase, int T, int t0, int ch) {
;     ...
;     for (int i = 0; i < NL; ++i) { const int s = t0 - HW + i; const v4u z = {0u, 0u, 0u, 0u}; x[i] = (s >= 0 && s < T) ? *(const v4u*)(PROJ + (size_t)(pbase + s) * INW + 3 * ATTW + 8 * ch) : z; }
;     float S[8];
; #pragma unroll
;     for (int c = 0; c < 8; ++c) S[c] = 0.f;
;     ...
; #pragma unroll
;     for (int i = 0; i < 2 * HW; ++i) POOL_ADD(+, x[i]);
; #pragma unroll
;     for (int k = 0; k < 4; ++k) {
;         if (k > 0) { POOL_ADD(-, x[k - 1]); POOL_ADD(+, x[k - 1 + 2 * HW]); }
;         const int t = t0 + k; const float ic = 1.0f / (float)(min(t + HW, T) - max(t - HW, 0)); const v4u w = x[HW + k];
;         v4u ow; ow.x = pk2(S[0] * ic - bflo(w.x), S[1] * ic - bfhi(w.x)); ow.y = pk2(S[2] * ic - bflo(w.y), S[3] * ic - bfhi(w.y));
;         ow.z = pk2(S[4] * ic - bflo(w.z), S[5] * ic - bfhi(w.z)); ow.w = pk2(S[6] * ic - bflo(w.w), S[7] * ic - bfhi(w.w));
;         *(v4u*)(CAT + blk_off(pbase + t, ATTW + 8 * ch, D)) = ow;
	v_pk_fma_f32 v[48:49], v[2:3], v[56:57], v[48:49] op_sel_hi:[0,1,1] neg_lo:[0,0,1] neg_hi:[0,0,1]
	v_add3_u32 v100, v100, v106, s15
	v_bfe_u32 v106, v45, 16, 1
	v_add_u32_e32 v63, 2, v63
	v_bfe_u32 v2, v49, 16, 1
	v_bfe_u32 v105, v101, 16, 1
	v_add3_u32 v45, v45, v106, s15
	v_cvt_f32_i32_e32 v63, v63
	v_add3_u32 v101, v101, v105, s15
	v_add3_u32 v2, v49, v2, s15
	v_bfe_u32 v105, v44, 16, 1
	v_lshrrev_b32_e32 v45, 16, v45
	v_bfe_u32 v104, v48, 16, 1
	v_add3_u32 v44, v44, v105, s15
	v_and_or_b32 v45, v2, s90, v45
	v_ashrrev_i32_e32 v2, 4, v82
	v_add3_u32 v48, v48, v104, s15
	v_lshrrev_b32_e32 v44, 16, v44
	v_and_b32_e32 v2, -16, v2
	v_and_or_b32 v44, v48, s90, v44
	v_add_u32_e32 v48, v2, v173
	v_lshlrev_b32_e32 v2, 6, v82
	v_div_scale_f32 v82, s[74:75], v63, v63, 1.0
	v_bfe_u32 v49, v42, 16, 1
	v_rcp_f32_e32 v83, v82
	v_add3_u32 v42, v42, v49, s15
	v_ashrrev_i32_e32 v49, 31, v48
	v_bfe_u32 v104, v43, 16, 1
	v_and_or_b32 v2, v2, s63, v174
	v_lshlrev_b64 v[48:49], 15, v[48:49]
	v_add3_u32 v43, v43, v104, s15
	v_lshl_add_u64 v[48:49], s[2:3], 0, v[48:49]
	v_lshlrev_b32_e32 v2, 1, v2
	v_lshrrev_b32_e32 v42, 16, v42
	v_lshrrev_b32_e32 v43, 16, v43
	v_lshl_add_u64 v[48:49], v[48:49], 0, v[2:3]
	v_fma_f32 v2, -v82, v83, 1.0
	v_and_or_b32 v43, v101, s90, v43
	v_and_or_b32 v42, v100, s90, v42
	v_fmac_f32_e32 v83, v2, v83
	v_div_scale_f32 v2, vcc, 1.0, v63, 1.0
	global_store_dwordx4 v[48:49], v[42:45], off sc1
	v_pk_add_f32 v[48:49], v[90:91], v[60:61] neg_lo:[0,1] neg_hi:[0,1]
	v_and_b32_e32 v61, 0xffff0000, v39
	v_mul_f32_e32 v42, v2, v83
	v_fma_f32 v43, -v82, v42, v2
	v_fmac_f32_e32 v42, v43, v83
	v_fma_f32 v2, -v82, v42, v2
	v_div_fmas_f32 v2, v2, v83, v42
	v_and_b32_e32 v60, 0xffff0000, v38
	v_div_fixup_f32 v2, v2, v63, 1.0
	v_pk_add_f32 v[42:43], v[86:87], v[98:99] neg_lo:[0,1] neg_hi:[0,1]
	v_pk_add_f32 v[48:49], v[48:49], v[60:61]
	v_pk_add_f32 v[84:85], v[94:95], v[84:85] neg_lo:[0,1] neg_hi:[0,1]
	v_lshlrev_b32_e32 v87, 16, v41
	v_lshlrev_b32_e32 v86, 16, v40
	v_lshlrev_b32_e32 v45, 16, v39
	v_lshlrev_b32_e32 v44, 16, v38
	v_pk_fma_f32 v[82:83], v[2:3], v[48:49], v[92:93] op_sel_hi:[0,1,1] neg_lo:[0,0,1] neg_hi:[0,0,1]
	v_pk_add_f32 v[84:85], v[84:85], v[86:87]
	v_pk_add_f32 v[56:57], v[56:57], v[58:59] neg_lo:[0,1] neg_hi:[0,1]
	v_and_b32_e32 v59, 0xffff0000, v41
	v_and_b32_e32 v58, 0xffff0000, v40
	v_pk_add_f32 v[42:43], v[42:43], v[44:45]
	v_pk_add_f32 v[56:57], v[56:57], v[58:59]
	v_pk_fma_f32 v[40:41], v[2:3], v[84:85], v[102:103] op_sel_hi:[0,1,1] neg_lo:[0,0,1] neg_hi:[0,0,1]
	v_bfe_u32 v90, v83, 16, 1
	v_pk_fma_f32 v[38:39], v[2:3], v[42:43], v[88:89] op_sel_hi:[0,1,1] neg_lo:[0,0,1] neg_hi:[0,0,1]
	v_pk_fma_f32 v[88:89], v[2:3], v[56:57], v[96:97] op_sel_hi:[0,1,1] neg_lo:[0,0,1] neg_hi:[0,0,1]
	v_add3_u32 v83, v83, v90, s15
	v_bfe_u32 v90, v40, 16, 1
	v_bfe_u32 v63, v88, 16, 1
	v_add3_u32 v40, v40, v90, s15
	v_add3_u32 v63, v88, v63, s15
	v_lshrrev_b32_e32 v40, 16, v40
	v_bfe_u32 v91, v82, 16, 1
	v_and_or_b32 v40, v63, s90, v40
	v_add_u32_e32 v63, 5, v196
	v_add3_u32 v82, v82, v91, s15
	v_bfe_u32 v91, v41, 16, 1
	v_min_u32_e32 v63, s28, v63
	v_bfe_u32 v2, v89, 16, 1
	v_add3_u32 v41, v41, v91, s15
	v_sub_u32_e32 v63, v63, v65
	v_add3_u32 v2, v89, v2, s15
	v_bfe_u32 v88, v38, 16, 1
	v_lshrrev_b32_e32 v41, 16, v41
	v_add_u32_e32 v63, 2, v63
	v_bfe_u32 v89, v39, 16, 1
	v_add3_u32 v38, v38, v88, s15
	v_and_or_b32 v41, v2, s90, v41
	v_ashrrev_i32_e32 v2, 4, v64
	v_cvt_f32_i32_e32 v63, v63
	v_add3_u32 v39, v39, v89, s15
	v_lshrrev_b32_e32 v38, 16, v38
	v_and_b32_e32 v2, -16, v2
	v_lshrrev_b32_e32 v39, 16, v39
	v_and_or_b32 v38, v82, s90, v38
	v_add_u32_e32 v82, v2, v173
	v_and_or_b32 v39, v83, s90, v39
	v_ashrrev_i32_e32 v83, 31, v82
	v_lshlrev_b32_e32 v2, 6, v64
	v_lshlrev_b64 v[64:65], 15, v[82:83]
	v_div_scale_f32 v82, s[74:75], v63, v63, 1.0
	v_rcp_f32_e32 v83, v82
	v_and_or_b32 v2, v2, s63, v174
	v_lshl_add_u64 v[64:65], s[2:3], 0, v[64:65]
	v_lshlrev_b32_e32 v2, 1, v2
	v_lshl_add_u64 v[64:65], v[64:65], 0, v[2:3]
	v_fma_f32 v2, -v82, v83, 1.0
	v_fmac_f32_e32 v83, v2, v83
	v_div_scale_f32 v2, vcc, 1.0, v63, 1.0
	global_store_dwordx4 v[64:65], v[38:41], off sc1
	s_nop 1
	v_mul_f32_e32 v38, v2, v83
	v_fma_f32 v39, -v82, v38, v2
	v_fmac_f32_e32 v38, v39, v83
	v_fma_f32 v2, -v82, v38, v2
	v_div_fmas_f32 v2, v2, v83, v38
	v_pk_add_f32 v[38:39], v[42:43], v[52:53] neg_lo:[0,1] neg_hi:[0,1]
	v_lshlrev_b32_e32 v41, 16, v35
	v_lshlrev_b32_e32 v40, 16, v34
	v_pk_add_f32 v[38:39], v[38:39], v[40:41]
	v_pk_add_f32 v[40:41], v[48:49], v[50:51] neg_lo:[0,1] neg_hi:[0,1]
	v_and_b32_e32 v35, 0xffff0000, v35
	v_and_b32_e32 v34, 0xffff0000, v34
	v_pk_add_f32 v[34:35], v[40:41], v[34:35]
	v_pk_add_f32 v[40:41], v[84:85], v[54:55] neg_lo:[0,1] neg_hi:[0,1]
	v_lshlrev_b32_e32 v43, 16, v37
	v_lshlrev_b32_e32 v42, 16, v36
	v_pk_add_f32 v[40:41], v[40:41], v[42:43]
	v_pk_add_f32 v[42:43], v[56:57], v[46:47] neg_lo:[0,1] neg_hi:[0,1]
	v_and_b32_e32 v37, 0xffff0000, v37
	v_and_b32_e32 v36, 0xffff0000, v36
	v_div_fixup_f32 v2, v2, v63, 1.0
	v_pk_add_f32 v[36:37], v[42:43], v[36:37]
	v_pk_fma_f32 v[34:35], v[2:3], v[34:35], v[60:61] op_sel_hi:[0,1,1] neg_lo:[0,0,1] neg_hi:[0,0,1]
	v_pk_fma_f32 v[36:37], v[2:3], v[36:37], v[58:59] op_sel_hi:[0,1,1] neg_lo:[0,0,1] neg_hi:[0,0,1]
	v_pk_fma_f32 v[38:39], v[2:3], v[38:39], v[44:45] op_sel_hi:[0,1,1] neg_lo:[0,0,1] neg_hi:[0,0,1]
	v_pk_fma_f32 v[40:41], v[2:3], v[40:41], v[86:87] op_sel_hi:[0,1,1] neg_lo:[0,0,1] neg_hi:[0,0,1]
	v_bfe_u32 v2, v37, 16, 1
	v_bfe_u32 v44, v34, 16, 1
	v_add3_u32 v34, v34, v44, s15
	v_add3_u32 v2, v37, v2, s15
	v_bfe_u32 v37, v38, 16, 1
	v_bfe_u32 v44, v41, 16, 1
	v_add3_u32 v41, v41, v44, s15
	v_add3_u32 v37, v38, v37, s15
	v_bfe_u32 v42, v36, 16, 1
	v_lshrrev_b32_e32 v38, 16, v37
	v_lshrrev_b32_e32 v37, 16, v41
	v_add3_u32 v36, v36, v42, s15
	v_bfe_u32 v42, v39, 16, 1
	v_and_or_b32 v37, v2, s90, v37
	v_ashrrev_i32_e32 v2, 4, v62
	v_bfe_u32 v43, v35, 16, 1
	v_add3_u32 v39, v39, v42, s15
	v_and_b32_e32 v2, -16, v2
	v_add3_u32 v35, v35, v43, s15
	v_lshrrev_b32_e32 v39, 16, v39
	v_and_or_b32 v34, v34, s90, v38
	v_add_u32_e32 v38, v2, v173
	v_bfe_u32 v43, v40, 16, 1
	v_and_or_b32 v35, v35, s90, v39
	v_ashrrev_i32_e32 v39, 31, v38
	v_lshlrev_b32_e32 v2, 6, v62
	v_add3_u32 v40, v40, v43, s15
	v_and_or_b32 v2, v2, s63, v174
	v_lshlrev_b64 v[38:39], 15, v[38:39]
	v_lshrrev_b32_e32 v40, 16, v40
	v_lshl_add_u64 v[38:39], s[2:3], 0, v[38:39]
	v_lshlrev_b32_e32 v2, 1, v2
	v_and_or_b32 v36, v36, s90, v40
	v_lshl_add_u64 v[38:39], v[38:39], 0, v[2:3]
	global_store_dwordx4 v[38:39], v[34:37], off sc1

; __device__ __forceinline__ unsigned pk2(float lo, float hi) { return f2bf(lo) | (f2bf(hi) << 16); }
; __device__ __forceinline__ size_t blk_off(int row, int col, int K) { return ((size_t)((row >> 8) * (K >> 6) + (col >> 6)) << 14) + (size_t)(((row & 255) << 6) + (col & 63)); }
; #define POOL_ADD(sgn, VV) do { S[0] += sgn bflo((VV).x); S[1] += sgn bfhi((VV).x); S[2] += sgn bflo((VV).y); S[3] += sgn bfhi((VV).y); S[4] += sgn bflo((VV).z); S[5] += sgn bfhi((VV).z); S[6] += sgn bflo((VV).w); S[7] += sgn bfhi((VV).w); } while (0)
; template <int HW> __device__ __forceinline__ void pool_group(const bf16* PROJ, bf16* CAT, int pbase, int T, int t0, int ch) {
;     ...
;     for (int i = 0; i < NL; ++i) { const int s = t0 - HW + i; const v4u z = {0u, 0u, 0u, 0u}; x[i] = (s >= 0 && s < T) ? *(const v4u*)(PROJ + (size_t)(pbase + s) * INW + 3 * ATTW + 8 * ch) : z; }
;     float S[8];
; #pragma unroll
;     for (int c = 0; c < 8; ++c) S[c] = 0.f;
;     ...
; #pragma unroll
;     for (int i = 0; i < 2 * HW; ++i) POOL_ADD(+, x[i]);
; #pragma unroll
;     for (int k = 0; k < 4; ++k) {
;         if (k > 0) { POOL_ADD(-, x[k - 1]); POOL_ADD(+, x[k - 1 + 2 * HW]); }
;         const int t = t0 + k; const float ic = 1.0f / (float)(min(t + HW, T) - max(t - HW, 0)); const v4u w = x[HW + k];
;         v4u ow; ow.x = pk2(S[0] * ic - bflo(w.x), S[1] * ic - bfhi(w.x)); ow.y = pk2(S[2] * ic - bflo(w.y), S[3] * ic - bfhi(w.y));
;         ow.z = pk2(S[4] * ic - bflo(w.z), S[5] * ic - bfhi(w.z)); ow.w = pk2(S[6] * ic - bflo(w.w), S[7] * ic - bfhi(w.w));
;         *(v4u*)(CAT + blk_off(pbase + t, ATTW + 8 * ch, D)) = ow;
.LBB0_355:
	s_or_b64 exec, exec, s[70:71]
	s_waitcnt vmcnt(0)
	v_lshlrev_b32_e32 v166, 16, v82
	v_and_b32_e32 v164, 0xffff0000, v82
	v_lshlrev_b32_e32 v162, 16, v84
	v_and_b32_e32 v160, 0xffff0000, v84
	v_lshlrev_b32_e32 v84, 16, v94
	v_and_b32_e32 v82, 0xffff0000, v94
	v_min_u32_e32 v2, s28, v2
	v_sub_u32_e64 v94, v196, 8 clamp
	v_sub_u32_e32 v2, v2, v94
	v_cvt_f32_i32_e32 v2, v2
	v_lshlrev_b32_e32 v167, 16, v83
	v_and_b32_e32 v165, 0xffff0000, v83
	v_lshlrev_b32_e32 v163, 16, v85
	v_div_scale_f32 v94, s[70:71], v2, v2, 1.0
	v_and_b32_e32 v161, 0xffff0000, v85
	v_lshlrev_b32_e32 v85, 16, v95
	v_and_b32_e32 v83, 0xffff0000, v95
	v_rcp_f32_e32 v95, v94
	v_lshlrev_b32_e32 v158, 16, v58
	v_and_b32_e32 v156, 0xffff0000, v58
	v_lshlrev_b32_e32 v154, 16, v60
	v_and_b32_e32 v152, 0xffff0000, v60
	v_lshlrev_b32_e32 v60, 16, v96
	v_and_b32_e32 v58, 0xffff0000, v96
	v_fma_f32 v96, -v94, v95, 1.0
	v_fmac_f32_e32 v95, v96, v95
	v_div_scale_f32 v96, vcc, 1.0, v2, 1.0
	v_lshlrev_b32_e32 v159, 16, v59
	v_and_b32_e32 v157, 0xffff0000, v59
	v_lshlrev_b32_e32 v155, 16, v61
	v_and_b32_e32 v153, 0xffff0000, v61
	v_lshlrev_b32_e32 v61, 16, v97
	v_and_b32_e32 v59, 0xffff0000, v97
	v_mul_f32_e32 v97, v96, v95
	v_fma_f32 v199, -v94, v97, v96
	v_fmac_f32_e32 v97, v199, v95
	v_fma_f32 v94, -v94, v97, v96
	v_pk_add_f32 v[200:201], v[166:167], 0 op_sel_hi:[1,0]
	v_div_fmas_f32 v94, v94, v95, v97
	v_pk_add_f32 v[202:203], v[164:165], 0 op_sel_hi:[1,0]
	v_div_fixup_f32 v2, v94, v2, 1.0
	v_pk_add_f32 v[94:95], v[200:201], v[158:159]
	v_lshlrev_b32_e32 v97, 16, v35
	v_pk_add_f32 v[94:95], v[94:95], v[84:85]
	v_lshlrev_b32_e32 v96, 16, v34
	v_pk_add_f32 v[202:203], v[202:203], v[156:157]
	v_pk_add_f32 v[94:95], v[94:95], v[96:97]
	v_lshlrev_b32_e32 v97, 16, v43
	v_lshlrev_b32_e32 v96, 16, v42
	v_pk_add_f32 v[202:203], v[202:203], v[82:83]
	v_and_b32_e32 v35, 0xffff0000, v35
	v_and_b32_e32 v34, 0xffff0000, v34
	v_pk_add_f32 v[94:95], v[94:95], v[96:97]
	v_lshlrev_b32_e32 v97, 16, v39
	v_lshlrev_b32_e32 v96, 16, v38
	v_pk_add_f32 v[34:35], v[202:203], v[34:35]
	v_and_b32_e32 v43, 0xffff0000, v43
	v_and_b32_e32 v42, 0xffff0000, v42
	v_pk_add_f32 v[94:95], v[94:95], v[96:97]
	v_lshlrev_b32_e32 v97, 16, v51
	v_lshlrev_b32_e32 v96, 16, v50
	v_pk_add_f32 v[34:35], v[34:35], v[42:43]
	v_and_b32_e32 v39, 0xffff0000, v39
	v_and_b32_e32 v38, 0xffff0000, v38
	v_pk_add_f32 v[94:95], v[94:95], v[96:97]
	v_lshlrev_b32_e32 v97, 16, v47
	v_lshlrev_b32_e32 v96, 16, v46
	v_pk_add_f32 v[34:35], v[34:35], v[38:39]
	v_and_b32_e32 v39, 0xffff0000, v51
	v_and_b32_e32 v38, 0xffff0000, v50
	v_lshlrev_b32_e32 v217, 16, v103
	v_lshlrev_b32_e32 v216, 16, v102
	v_pk_add_f32 v[200:201], v[94:95], v[96:97]
	v_pk_add_f32 v[34:35], v[34:35], v[38:39]
	v_and_b32_e32 v39, 0xffff0000, v47
	v_and_b32_e32 v38, 0xffff0000, v46
	v_and_b32_e32 v219, 0xffff0000, v103
	v_and_b32_e32 v218, 0xffff0000, v102
	v_lshlrev_b32_e32 v103, 16, v55
	v_lshlrev_b32_e32 v102, 16, v54
	v_pk_add_f32 v[200:201], v[200:201], v[216:217]
	v_pk_add_f32 v[38:39], v[34:35], v[38:39]
	v_lshlrev_b32_e32 v97, 16, v99
	v_lshlrev_b32_e32 v96, 16, v98
	v_pk_add_f32 v[200:201], v[200:201], v[102:103]
	v_and_b32_e32 v51, 0xffff0000, v55
	v_and_b32_e32 v50, 0xffff0000, v54
	v_pk_add_f32 v[38:39], v[38:39], v[218:219]
	v_lshlrev_b32_e32 v95, 16, v91
	v_lshlrev_b32_e32 v94, 16, v90
	v_pk_add_f32 v[200:201], v[200:201], v[96:97]
	v_and_b32_e32 v43, 0xffff0000, v99
	v_and_b32_e32 v42, 0xffff0000, v98
	v_pk_add_f32 v[38:39], v[38:39], v[50:51]
	v_lshlrev_b32_e32 v209, 16, v123
	v_lshlrev_b32_e32 v208, 16, v122
	v_pk_add_f32 v[200:201], v[200:201], v[94:95]
	v_and_b32_e32 v35, 0xffff0000, v91
	v_and_b32_e32 v34, 0xffff0000, v90
	v_pk_add_f32 v[38:39], v[38:39], v[42:43]
	v_and_b32_e32 v211, 0xffff0000, v123
	v_and_b32_e32 v210, 0xffff0000, v122
	v_lshlrev_b32_e32 v212, 16, v118
	v_lshlrev_b32_e32 v213, 16, v119
	v_pk_add_f32 v[38:39], v[38:39], v[34:35]
	v_pk_add_f32 v[46:47], v[200:201], v[208:209]
	v_and_b32_e32 v118, 0xffff0000, v118
	v_and_b32_e32 v119, 0xffff0000, v119
	v_pk_add_f32 v[38:39], v[38:39], v[210:211]
	v_pk_add_f32 v[46:47], v[46:47], v[212:213]
	v_lshlrev_b32_e32 v55, 16, v115
	v_lshlrev_b32_e32 v54, 16, v114
	v_pk_add_f32 v[38:39], v[38:39], v[118:119]
	v_pk_add_f32 v[46:47], v[46:47], v[54:55]
	v_and_b32_e32 v55, 0xffff0000, v115
	v_and_b32_e32 v54, 0xffff0000, v114
	v_pk_add_f32 v[38:39], v[38:39], v[54:55]
	v_lshlrev_b32_e32 v55, 16, v111
	v_lshlrev_b32_e32 v54, 16, v110
	v_pk_add_f32 v[204:205], v[162:163], 0 op_sel_hi:[1,0]
	v_pk_add_f32 v[90:91], v[46:47], v[54:55]
	v_and_b32_e32 v47, 0xffff0000, v111
	v_and_b32_e32 v46, 0xffff0000, v110
	v_pk_add_f32 v[206:207], v[160:161], 0 op_sel_hi:[1,0]
	v_pk_add_f32 v[98:99], v[38:39], v[46:47]
	v_pk_add_f32 v[38:39], v[204:205], v[154:155]
	v_lshlrev_b32_e32 v47, 16, v37
	v_pk_add_f32 v[38:39], v[38:39], v[60:61]
	v_lshlrev_b32_e32 v46, 16, v36
	v_pk_add_f32 v[202:203], v[206:207], v[152:153]
	v_pk_add_f32 v[38:39], v[38:39], v[46:47]
	v_lshlrev_b32_e32 v47, 16, v45
	v_lshlrev_b32_e32 v46, 16, v44
	v_pk_add_f32 v[202:203], v[202:203], v[58:59]
	v_and_b32_e32 v37, 0xffff0000, v37
	v_and_b32_e32 v36, 0xffff0000, v36
	v_pk_add_f32 v[38:39], v[38:39], v[46:47]
	v_lshlrev_b32_e32 v47, 16, v41
	v_lshlrev_b32_e32 v46, 16, v40
	v_pk_add_f32 v[36:37], v[202:203], v[36:37]
	v_and_b32_e32 v45, 0xffff0000, v45
	v_and_b32_e32 v44, 0xffff0000, v44
	v_pk_add_f32 v[38:39], v[38:39], v[46:47]
	v_lshlrev_b32_e32 v47, 16, v53
	v_lshlrev_b32_e32 v46, 16, v52
	v_pk_add_f32 v[36:37], v[36:37], v[44:45]
	v_and_b32_e32 v41, 0xffff0000, v41
	v_and_b32_e32 v40, 0xffff0000, v40
	v_pk_add_f32 v[38:39], v[38:39], v[46:47]
; __device__ __forceinline__ unsigned pk2(float lo, float hi) { return f2bf(lo) | (f2bf(hi) << 16); }
; __device__ __forceinline__ size_t blk_off(int row, int col, int K) { return ((size_t)((row >> 8) * (K >> 6) + (col >> 6)) << 14) + (size_t)(((row & 255) << 6) + (col & 63)); }
; #define POOL_ADD(sgn, VV) do { S[0] += sgn bflo((VV).x); S[1] += sgn bfhi((VV).x); S[2] += sgn bflo((VV).y); S[3] += sgn bfhi((VV).y); S[4] += sgn bflo((VV).z); S[5] += sgn bfhi((VV).z); S[6] += sgn bflo((VV).w); S[7] += sgn bfhi((VV).w); } while (0)
; template <int HW> __device__ __forceinline__ void pool_group(const bf16* PROJ, bf16* CAT, int pbase, int T, int t0, int ch) {
;     constexpr int NL = 2 * HW + 3;
;     v4u x[NL];
; #pragma unroll
;     for (int i = 0; i < NL; ++i) { const int s = t0 - HW + i; const v4u z = {0u, 0u, 0u, 0u}; x[i] = (s >= 0 && s < T) ? *(const v4u*)(PROJ + (size_t)(pbase + s) * INW + 3 * ATTW + 8 * ch) : z; }
;     float S[8];
; #pragma unroll
;     for (int c = 0; c < 8; ++c) S[c] = 0.f;
;     ...
; #pragma unroll
;     for (int i = 0; i < 2 * HW; ++i) POOL_ADD(+, x[i]);
; #pragma unroll
;     for (int k = 0; k < 4; ++k) {
;         if (k > 0) { POOL_ADD(-, x[k - 1]); POOL_ADD(+, x[k - 1 + 2 * HW]); }
;         const int t = t0 + k; const float ic = 1.0f / (float)(min(t + HW, T) - max(t - HW, 0)); const v4u w = x[HW + k];
;         v4u ow; ow.x = pk2(S[0] * ic - bflo(w.x), S[1] * ic - bfhi(w.x)); ow.y = pk2(S[2] * ic - bflo(w.y), S[3] * ic - bfhi(w.y));
;         ow.z = pk2(S[4] * ic - bflo(w.z), S[5] * ic - bfhi(w.z)); ow.w = pk2(S[6] * ic - bflo(w.w), S[7] * ic - bfhi(w.w));
;         *(v4u*)(CAT + blk_off(pbase + t, ATTW + 8 * ch, D)) = ow;
	v_lshlrev_b32_e32 v47, 16, v49
	v_lshlrev_b32_e32 v46, 16, v48
	v_pk_add_f32 v[36:37], v[36:37], v[40:41]
	v_and_b32_e32 v41, 0xffff0000, v53
	v_and_b32_e32 v40, 0xffff0000, v52
	v_lshlrev_b32_e32 v115, 16, v105
	v_lshlrev_b32_e32 v114, 16, v104
	v_pk_add_f32 v[118:119], v[38:39], v[46:47]
	v_pk_add_f32 v[36:37], v[36:37], v[40:41]
	v_and_b32_e32 v41, 0xffff0000, v49
	v_and_b32_e32 v40, 0xffff0000, v48
	v_and_b32_e32 v105, 0xffff0000, v105
	v_and_b32_e32 v104, 0xffff0000, v104
	v_lshlrev_b32_e32 v201, 16, v57
	v_lshlrev_b32_e32 v200, 16, v56
	v_pk_add_f32 v[118:119], v[118:119], v[114:115]
	v_pk_add_f32 v[40:41], v[36:37], v[40:41]
	v_lshlrev_b32_e32 v47, 16, v101
	v_lshlrev_b32_e32 v46, 16, v100
	v_pk_add_f32 v[118:119], v[118:119], v[200:201]
	v_and_b32_e32 v45, 0xffff0000, v57
	v_and_b32_e32 v44, 0xffff0000, v56
	v_pk_add_f32 v[40:41], v[40:41], v[104:105]
	v_lshlrev_b32_e32 v39, 16, v93
	v_lshlrev_b32_e32 v38, 16, v92
	v_pk_add_f32 v[118:119], v[118:119], v[46:47]
	v_and_b32_e32 v57, 0xffff0000, v101
	v_and_b32_e32 v56, 0xffff0000, v100
	v_pk_add_f32 v[40:41], v[40:41], v[44:45]
	v_lshlrev_b32_e32 v123, 16, v125
	v_lshlrev_b32_e32 v122, 16, v124
	v_pk_add_f32 v[118:119], v[118:119], v[38:39]
	v_and_b32_e32 v37, 0xffff0000, v93
	v_and_b32_e32 v36, 0xffff0000, v92
	v_pk_add_f32 v[40:41], v[40:41], v[56:57]
	v_and_b32_e32 v125, 0xffff0000, v125
	v_and_b32_e32 v124, 0xffff0000, v124
	v_lshlrev_b32_e32 v214, 16, v120
	v_lshlrev_b32_e32 v215, 16, v121
	v_pk_add_f32 v[40:41], v[40:41], v[36:37]
	v_pk_add_f32 v[48:49], v[118:119], v[122:123]
	v_and_b32_e32 v120, 0xffff0000, v120
	v_and_b32_e32 v121, 0xffff0000, v121
	v_pk_add_f32 v[40:41], v[40:41], v[124:125]
	v_pk_add_f32 v[48:49], v[48:49], v[214:215]
	v_lshlrev_b32_e32 v53, 16, v117
	v_lshlrev_b32_e32 v52, 16, v116
	v_pk_add_f32 v[40:41], v[40:41], v[120:121]
	v_pk_add_f32 v[48:49], v[48:49], v[52:53]
	v_and_b32_e32 v53, 0xffff0000, v117
	v_and_b32_e32 v52, 0xffff0000, v116
	v_pk_add_f32 v[40:41], v[40:41], v[52:53]
	v_lshlrev_b32_e32 v53, 16, v113
	v_lshlrev_b32_e32 v52, 16, v112
	v_pk_add_f32 v[48:49], v[48:49], v[52:53]
	v_and_b32_e32 v53, 0xffff0000, v113
	v_and_b32_e32 v52, 0xffff0000, v112
	v_pk_add_f32 v[40:41], v[40:41], v[52:53]
	v_pk_fma_f32 v[110:111], v[2:3], v[98:99], v[218:219] op_sel_hi:[0,1,1] neg_lo:[0,0,1] neg_hi:[0,0,1]
	v_pk_fma_f32 v[92:93], v[2:3], v[40:41], v[104:105] op_sel_hi:[0,1,1] neg_lo:[0,0,1] neg_hi:[0,0,1]
	v_pk_fma_f32 v[54:55], v[2:3], v[90:91], v[216:217] op_sel_hi:[0,1,1] neg_lo:[0,0,1] neg_hi:[0,0,1]
	v_pk_fma_f32 v[52:53], v[2:3], v[48:49], v[114:115] op_sel_hi:[0,1,1] neg_lo:[0,0,1] neg_hi:[0,0,1]
	v_bfe_u32 v100, v92, 16, 1
	v_bfe_u32 v104, v110, 16, 1
	v_add3_u32 v104, v110, v104, s15
	v_add3_u32 v92, v92, v100, s15
	v_bfe_u32 v100, v55, 16, 1
	v_bfe_u32 v110, v53, 16, 1
	v_bfe_u32 v2, v93, 16, 1
	v_bfe_u32 v101, v111, 16, 1
	v_add3_u32 v53, v53, v110, s15
	v_add3_u32 v55, v55, v100, s15
	v_add3_u32 v101, v111, v101, s15
	v_add3_u32 v2, v93, v2, s15
	v_lshrrev_b32_e32 v100, 16, v55
	v_lshrrev_b32_e32 v53, 16, v53
	v_and_or_b32 v55, v2, s90, v53
	v_and_or_b32 v53, v101, s90, v100
	v_min_u32_e32 v100, s28, v198
	v_sub_u32_e64 v101, v197, 8 clamp
	v_sub_u32_e32 v100, v100, v101
	v_bfe_u32 v105, v52, 16, 1
	v_cvt_f32_i32_e32 v100, v100
	v_bfe_u32 v93, v54, 16, 1
	v_add3_u32 v52, v52, v105, s15
	v_add3_u32 v54, v54, v93, s15
	v_lshrrev_b32_e32 v52, 16, v52
	v_add_u32_e32 v2, s43, v196
	v_lshrrev_b32_e32 v93, 16, v54
	v_and_or_b32 v54, v92, s90, v52
	v_ashrrev_i32_e32 v92, 4, v2
	v_and_b32_e32 v92, -16, v92
	v_div_scale_f32 v101, s[70:71], v100, v100, 1.0
	v_and_or_b32 v52, v104, s90, v93
	v_add_u32_e32 v92, v92, v173
	v_rcp_f32_e32 v104, v101
	v_ashrrev_i32_e32 v93, 31, v92
	v_lshlrev_b32_e32 v2, 6, v2
	v_and_or_b32 v2, v2, s63, v174
	v_lshlrev_b64 v[92:93], 15, v[92:93]
	v_lshl_add_u64 v[92:93], s[2:3], 0, v[92:93]
	v_lshlrev_b32_e32 v2, 1, v2
	v_lshl_add_u64 v[92:93], v[92:93], 0, v[2:3]
	v_fma_f32 v2, -v101, v104, 1.0
	v_fmac_f32_e32 v104, v2, v104
	v_div_scale_f32 v2, vcc, 1.0, v100, 1.0
	global_store_dwordx4 v[92:93], v[52:55], off sc1
	v_pk_add_f32 v[48:49], v[48:49], v[162:163] neg_lo:[0,1] neg_hi:[0,1]
	v_lshlrev_b32_e32 v93, 16, v109
	v_mul_f32_e32 v52, v2, v104
	v_fma_f32 v53, -v101, v52, v2
	v_fmac_f32_e32 v52, v53, v104
	v_fma_f32 v2, -v101, v52, v2
	v_div_fmas_f32 v2, v2, v104, v52
	v_pk_add_f32 v[52:53], v[90:91], v[166:167] neg_lo:[0,1] neg_hi:[0,1]
	v_lshlrev_b32_e32 v55, 16, v107
	v_lshlrev_b32_e32 v54, 16, v106
	v_lshlrev_b32_e32 v92, 16, v108
	v_pk_add_f32 v[52:53], v[52:53], v[54:55]
	v_pk_add_f32 v[54:55], v[98:99], v[164:165] neg_lo:[0,1] neg_hi:[0,1]
	v_and_b32_e32 v91, 0xffff0000, v107
	v_and_b32_e32 v90, 0xffff0000, v106
	v_pk_add_f32 v[92:93], v[48:49], v[92:93]
	v_pk_add_f32 v[40:41], v[40:41], v[160:161] neg_lo:[0,1] neg_hi:[0,1]
	v_and_b32_e32 v49, 0xffff0000, v109
	v_and_b32_e32 v48, 0xffff0000, v108
	v_div_fixup_f32 v2, v2, v100, 1.0
	v_pk_add_f32 v[54:55], v[54:55], v[90:91]
	v_pk_add_f32 v[40:41], v[40:41], v[48:49]
	v_pk_fma_f32 v[50:51], v[2:3], v[54:55], v[50:51] op_sel_hi:[0,1,1] neg_lo:[0,0,1] neg_hi:[0,0,1]
	v_pk_fma_f32 v[44:45], v[2:3], v[40:41], v[44:45] op_sel_hi:[0,1,1] neg_lo:[0,0,1] neg_hi:[0,0,1]
	v_pk_fma_f32 v[90:91], v[2:3], v[52:53], v[102:103] op_sel_hi:[0,1,1] neg_lo:[0,0,1] neg_hi:[0,0,1]
	v_pk_fma_f32 v[48:49], v[2:3], v[92:93], v[200:201] op_sel_hi:[0,1,1] neg_lo:[0,0,1] neg_hi:[0,0,1]
	v_bfe_u32 v98, v44, 16, 1
	v_bfe_u32 v100, v50, 16, 1
	v_bfe_u32 v2, v45, 16, 1
	v_add3_u32 v100, v50, v100, s15
	v_add3_u32 v44, v44, v98, s15
	v_bfe_u32 v50, v91, 16, 1
	v_bfe_u32 v98, v49, 16, 1
; __device__ __forceinline__ unsigned pk2(float lo, float hi) { return f2bf(lo) | (f2bf(hi) << 16); }
; __device__ __forceinline__ size_t blk_off(int row, int col, int K) { return ((size_t)((row >> 8) * (K >> 6) + (col >> 6)) << 14) + (size_t)(((row & 255) << 6) + (col & 63)); }
; #define POOL_ADD(sgn, VV) do { S[0] += sgn bflo((VV).x); S[1] += sgn bfhi((VV).x); S[2] += sgn bflo((VV).y); S[3] += sgn bfhi((VV).y); S[4] += sgn bflo((VV).z); S[5] += sgn bfhi((VV).z); S[6] += sgn bflo((VV).w); S[7] += sgn bfhi((VV).w); } while (0)
; template <int HW> __device__ __forceinline__ void pool_group(const bf16* PROJ, bf16* CAT, int pbase, int T, int t0, int ch) {
;     ...
;     for (int k = 0; k < 4; ++k) {
;         if (k > 0) { POOL_ADD(-, x[k - 1]); POOL_ADD(+, x[k - 1 + 2 * HW]); }
;         const int t = t0 + k; const float ic = 1.0f / (float)(min(t + HW, T) - max(t - HW, 0)); const v4u w = x[HW + k];
;         v4u ow; ow.x = pk2(S[0] * ic - bflo(w.x), S[1] * ic - bfhi(w.x)); ow.y = pk2(S[2] * ic - bflo(w.y), S[3] * ic - bfhi(w.y));
;         ow.z = pk2(S[4] * ic - bflo(w.z), S[5] * ic - bfhi(w.z)); ow.w = pk2(S[6] * ic - bflo(w.w), S[7] * ic - bfhi(w.w));
;         *(v4u*)(CAT + blk_off(pbase + t, ATTW + 8 * ch, D)) = ow;
	v_bfe_u32 v99, v51, 16, 1
	v_add3_u32 v2, v45, v2, s15
	v_bfe_u32 v45, v90, 16, 1
	v_add3_u32 v49, v49, v98, s15
	v_add3_u32 v50, v91, v50, s15
	v_add3_u32 v99, v51, v99, s15
	v_bfe_u32 v51, v48, 16, 1
	v_add3_u32 v45, v90, v45, s15
	v_lshrrev_b32_e32 v90, 16, v50
	v_lshrrev_b32_e32 v49, 16, v49
	v_add3_u32 v48, v48, v51, s15
	v_and_or_b32 v51, v2, s90, v49
	v_and_or_b32 v49, v99, s90, v90
	v_min_u32_e32 v90, s28, v147
	v_sub_u32_e64 v91, v151, 8 clamp
	v_sub_u32_e32 v90, v90, v91
	v_cvt_f32_i32_e32 v90, v90
	v_ashrrev_i32_e32 v2, 4, v150
	v_lshrrev_b32_e32 v48, 16, v48
	v_and_b32_e32 v2, -16, v2
	v_div_scale_f32 v91, s[70:71], v90, v90, 1.0
	v_lshrrev_b32_e32 v45, 16, v45
	v_and_or_b32 v50, v44, s90, v48
	v_add_u32_e32 v44, v2, v173
	v_rcp_f32_e32 v98, v91
	v_and_or_b32 v48, v100, s90, v45
	v_ashrrev_i32_e32 v45, 31, v44
	v_lshlrev_b32_e32 v2, 6, v150
	v_and_or_b32 v2, v2, s63, v174
	v_lshlrev_b64 v[44:45], 15, v[44:45]
	v_lshl_add_u64 v[44:45], s[2:3], 0, v[44:45]
	v_lshlrev_b32_e32 v2, 1, v2
	v_lshl_add_u64 v[44:45], v[44:45], 0, v[2:3]
	v_fma_f32 v2, -v91, v98, 1.0
	v_fmac_f32_e32 v98, v2, v98
	v_div_scale_f32 v2, vcc, 1.0, v90, 1.0
	global_store_dwordx4 v[44:45], v[48:51], off sc1
	v_mul_f32_e32 v44, v2, v98
	v_fma_f32 v45, -v91, v44, v2
	v_fmac_f32_e32 v44, v45, v98
	v_fma_f32 v2, -v91, v44, v2
	v_div_fmas_f32 v2, v2, v98, v44
	v_pk_add_f32 v[44:45], v[52:53], v[158:159] neg_lo:[0,1] neg_hi:[0,1]
	v_lshlrev_b32_e32 v49, 16, v87
	v_lshlrev_b32_e32 v48, 16, v86
	v_pk_add_f32 v[44:45], v[44:45], v[48:49]
	v_pk_add_f32 v[48:49], v[54:55], v[156:157] neg_lo:[0,1] neg_hi:[0,1]
	v_and_b32_e32 v51, 0xffff0000, v87
	v_and_b32_e32 v50, 0xffff0000, v86
	v_pk_add_f32 v[52:53], v[92:93], v[154:155] neg_lo:[0,1] neg_hi:[0,1]
	v_lshlrev_b32_e32 v55, 16, v89
	v_lshlrev_b32_e32 v54, 16, v88
	v_div_fixup_f32 v2, v2, v90, 1.0
	v_pk_add_f32 v[48:49], v[48:49], v[50:51]
	v_pk_add_f32 v[52:53], v[52:53], v[54:55]
	v_pk_add_f32 v[40:41], v[40:41], v[152:153] neg_lo:[0,1] neg_hi:[0,1]
	v_and_b32_e32 v55, 0xffff0000, v89
	v_and_b32_e32 v54, 0xffff0000, v88
	v_pk_fma_f32 v[42:43], v[2:3], v[48:49], v[42:43] op_sel_hi:[0,1,1] neg_lo:[0,0,1] neg_hi:[0,0,1]
	v_pk_add_f32 v[54:55], v[40:41], v[54:55]
	v_pk_fma_f32 v[50:51], v[2:3], v[44:45], v[96:97] op_sel_hi:[0,1,1] neg_lo:[0,0,1] neg_hi:[0,0,1]
	v_pk_fma_f32 v[40:41], v[2:3], v[52:53], v[46:47] op_sel_hi:[0,1,1] neg_lo:[0,0,1] neg_hi:[0,0,1]
	v_pk_fma_f32 v[46:47], v[2:3], v[54:55], v[56:57] op_sel_hi:[0,1,1] neg_lo:[0,0,1] neg_hi:[0,0,1]
	v_bfe_u32 v57, v43, 16, 1
	v_bfe_u32 v56, v46, 16, 1
	v_bfe_u32 v86, v42, 16, 1
	v_add3_u32 v57, v43, v57, s15
	v_bfe_u32 v43, v50, 16, 1
	v_add3_u32 v86, v42, v86, s15
	v_add3_u32 v42, v46, v56, s15
	v_bfe_u32 v46, v51, 16, 1
	v_add3_u32 v43, v50, v43, s15
	v_add_u32_e32 v50, 11, v196
	v_add3_u32 v46, v51, v46, s15
	v_min_u32_e32 v50, s28, v50
	v_sub_u32_e64 v51, v149, 8 clamp
	v_sub_u32_e32 v50, v50, v51
	v_bfe_u32 v56, v41, 16, 1
	v_cvt_f32_i32_e32 v50, v50
	v_bfe_u32 v2, v47, 16, 1
	v_add3_u32 v41, v41, v56, s15
	v_add3_u32 v2, v47, v2, s15
	v_bfe_u32 v47, v40, 16, 1
	v_lshrrev_b32_e32 v41, 16, v41
	v_add3_u32 v40, v40, v47, s15
	v_lshrrev_b32_e32 v47, 16, v43
	v_and_or_b32 v43, v2, s90, v41
	v_ashrrev_i32_e32 v2, 4, v148
	v_lshrrev_b32_e32 v46, 16, v46
	v_and_b32_e32 v2, -16, v2
	v_div_scale_f32 v51, s[70:71], v50, v50, 1.0
	v_lshrrev_b32_e32 v40, 16, v40
	v_and_or_b32 v41, v57, s90, v46
	v_add_u32_e32 v46, v2, v173
	v_rcp_f32_e32 v56, v51
	v_and_or_b32 v42, v42, s90, v40
	v_and_or_b32 v40, v86, s90, v47
	v_ashrrev_i32_e32 v47, 31, v46
	v_lshlrev_b32_e32 v2, 6, v148
	v_and_or_b32 v2, v2, s63, v174
	v_lshlrev_b64 v[46:47], 15, v[46:47]
	v_lshl_add_u64 v[46:47], s[2:3], 0, v[46:47]
	v_lshlrev_b32_e32 v2, 1, v2
	v_lshl_add_u64 v[46:47], v[46:47], 0, v[2:3]
	v_fma_f32 v2, -v51, v56, 1.0
	v_fmac_f32_e32 v56, v2, v56
	v_div_scale_f32 v2, vcc, 1.0, v50, 1.0
	global_store_dwordx4 v[46:47], v[40:43], off sc1
	v_and_b32_e32 v47, 0xffff0000, v65
	v_and_b32_e32 v46, 0xffff0000, v64
	v_mul_f32_e32 v40, v2, v56
	v_fma_f32 v41, -v51, v40, v2
	v_fmac_f32_e32 v40, v41, v56
	v_fma_f32 v2, -v51, v40, v2
	v_div_fmas_f32 v2, v2, v56, v40
	v_pk_add_f32 v[40:41], v[44:45], v[84:85] neg_lo:[0,1] neg_hi:[0,1]
	v_lshlrev_b32_e32 v43, 16, v63
	v_lshlrev_b32_e32 v42, 16, v62
	v_pk_add_f32 v[40:41], v[40:41], v[42:43]
	v_pk_add_f32 v[42:43], v[48:49], v[82:83] neg_lo:[0,1] neg_hi:[0,1]
	v_and_b32_e32 v45, 0xffff0000, v63
	v_and_b32_e32 v44, 0xffff0000, v62
	v_div_fixup_f32 v2, v2, v50, 1.0
	v_pk_add_f32 v[42:43], v[42:43], v[44:45]
	v_lshlrev_b32_e32 v45, 16, v65
	v_pk_fma_f32 v[34:35], v[2:3], v[42:43], v[34:35] op_sel_hi:[0,1,1] neg_lo:[0,0,1] neg_hi:[0,0,1]
	v_pk_add_f32 v[42:43], v[52:53], v[60:61] neg_lo:[0,1] neg_hi:[0,1]
	v_lshlrev_b32_e32 v44, 16, v64
	v_pk_add_f32 v[42:43], v[42:43], v[44:45]
	v_pk_add_f32 v[44:45], v[54:55], v[58:59] neg_lo:[0,1] neg_hi:[0,1]
	v_pk_fma_f32 v[40:41], v[2:3], v[40:41], v[94:95] op_sel_hi:[0,1,1] neg_lo:[0,0,1] neg_hi:[0,0,1]
	v_pk_add_f32 v[44:45], v[44:45], v[46:47]
	v_pk_fma_f32 v[38:39], v[2:3], v[42:43], v[38:39] op_sel_hi:[0,1,1] neg_lo:[0,0,1] neg_hi:[0,0,1]
	v_pk_fma_f32 v[36:37], v[2:3], v[44:45], v[36:37] op_sel_hi:[0,1,1] neg_lo:[0,0,1] neg_hi:[0,0,1]
	v_bfe_u32 v2, v37, 16, 1
	v_bfe_u32 v44, v34, 16, 1
	v_add3_u32 v34, v34, v44, s15
	v_add3_u32 v2, v37, v2, s15
	v_bfe_u32 v37, v40, 16, 1
	v_bfe_u32 v44, v39, 16, 1
	v_bfe_u32 v43, v35, 16, 1
	v_add3_u32 v39, v39, v44, s15
	v_add3_u32 v37, v40, v37, s15
	v_add3_u32 v35, v35, v43, s15
	v_bfe_u32 v43, v38, 16, 1
	v_lshrrev_b32_e32 v40, 16, v37
	v_lshrrev_b32_e32 v37, 16, v39
	v_bfe_u32 v42, v36, 16, 1
	v_add3_u32 v38, v38, v43, s15
	v_and_or_b32 v37, v2, s90, v37
	v_ashrrev_i32_e32 v2, 4, v146
	v_add3_u32 v36, v36, v42, s15
	v_lshrrev_b32_e32 v38, 16, v38
	v_and_b32_e32 v2, -16, v2
	v_and_or_b32 v36, v36, s90, v38
	v_add_u32_e32 v38, v2, v173
	v_bfe_u32 v42, v41, 16, 1
	v_ashrrev_i32_e32 v39, 31, v38
	v_lshlrev_b32_e32 v2, 6, v146
	v_add3_u32 v41, v41, v42, s15
	v_and_or_b32 v2, v2, s63, v174
	v_lshlrev_b64 v[38:39], 15, v[38:39]
	v_lshrrev_b32_e32 v41, 16, v41
	v_lshl_add_u64 v[38:39], s[2:3], 0, v[38:39]
	v_lshlrev_b32_e32 v2, 1, v2
	v_and_or_b32 v35, v35, s90, v41
	v_and_or_b32 v34, v34, s90, v40
	v_lshl_add_u64 v[38:39], v[38:39], 0, v[2:3]
	global_store_dwordx4 v[38:39], v[34:37], off sc1

; __device__ __forceinline__ unsigned pk2(float lo, float hi) { return f2bf(lo) | (f2bf(hi) << 16); }
; __device__ __forceinline__ size_t blk_off(int row, int col, int K) { return ((size_t)((row >> 8) * (K >> 6) + (col >> 6)) << 14) + (size_t)(((row & 255) << 6) + (col & 63)); }
; #define POOL_ADD(sgn, VV) do { S[0] += sgn bflo((VV).x); S[1] += sgn bfhi((VV).x); S[2] += sgn bflo((VV).y); S[3] += sgn bfhi((VV).y); S[4] += sgn bflo((VV).z); S[5] += sgn bfhi((VV).z); S[6] += sgn bflo((VV).w); S[7] += sgn bfhi((VV).w); } while (0)
; template <int HW> __device__ __forceinline__ void pool_group(const bf16* PROJ, bf16* CAT, int pbase, int T, int t0, int ch) {
;     ...
; #pragma unroll
;     for (int i = 0; i < NL; ++i) { const int s = t0 - HW + i; const v4u z = {0u, 0u, 0u, 0u}; x[i] = (s >= 0 && s < T) ? *(const v4u*)(PROJ + (size_t)(pbase + s) * INW + 3 * ATTW + 8 * ch) : z; }
;     float S[8];
; #pragma unroll
;     for (int c = 0; c < 8; ++c) S[c] = 0.f;
;     ...
; #pragma unroll
;     for (int i = 0; i < 2 * HW; ++i) POOL_ADD(+, x[i]);
; #pragma unroll
;     for (int k = 0; k < 4; ++k) {
;         if (k > 0) { POOL_ADD(-, x[k - 1]); POOL_ADD(+, x[k - 1 + 2 * HW]); }
;         const int t = t0 + k; const float ic = 1.0f / (float)(min(t + HW, T) - max(t - HW, 0)); const v4u w = x[HW + k];
;         v4u ow; ow.x = pk2(S[0] * ic - bflo(w.x), S[1] * ic - bfhi(w.x)); ow.y = pk2(S[2] * ic - bflo(w.y), S[3] * ic - bfhi(w.y));
;         ow.z = pk2(S[4] * ic - bflo(w.z), S[5] * ic - bfhi(w.z)); ow.w = pk2(S[6] * ic - bflo(w.w), S[7] * ic - bfhi(w.w));
;         *(v4u*)(CAT + blk_off(pbase + t, ATTW + 8 * ch, D)) = ow;
.LBB0_373:
	s_or_b64 exec, exec, s[70:71]
	v_min_u32_e32 v55, s28, v2
	v_sub_u32_e64 v61, v196, 1 clamp
	v_sub_u32_e32 v55, v55, v61
	v_cvt_f32_i32_e32 v55, v55
	s_waitcnt vmcnt(0)
	v_lshlrev_b32_e32 v63, 16, v51
	v_and_b32_e32 v51, 0xffff0000, v51
	v_and_b32_e32 v89, 0xffff0000, v47
	v_div_scale_f32 v61, s[70:71], v55, v55, 1.0
	v_rcp_f32_e32 v62, v61
	v_div_scale_f32 v64, vcc, 1.0, v55, 1.0
	v_and_b32_e32 v88, 0xffff0000, v46
	v_fma_f32 v65, -v61, v62, 1.0
	v_fmac_f32_e32 v62, v65, v62
	v_mul_f32_e32 v65, v64, v62
	v_fma_f32 v82, -v61, v65, v64
	v_fmac_f32_e32 v65, v82, v62
	v_fma_f32 v61, -v61, v65, v64
	v_div_fmas_f32 v61, v61, v62, v65
	v_lshlrev_b32_e32 v62, 16, v50
	v_and_b32_e32 v50, 0xffff0000, v50
	v_pk_add_f32 v[84:85], v[50:51], 0 op_sel_hi:[1,0]
	v_lshlrev_b32_e32 v93, 16, v53
	v_lshlrev_b32_e32 v92, 16, v52
	v_div_fixup_f32 v64, v61, v55, 1.0
	v_pk_add_f32 v[84:85], v[84:85], v[88:89]
	v_pk_add_f32 v[94:95], v[92:93], 0 op_sel_hi:[1,0]
	v_and_b32_e32 v53, 0xffff0000, v53
	v_and_b32_e32 v52, 0xffff0000, v52
	v_lshlrev_b32_e32 v99, 16, v49
	v_lshlrev_b32_e32 v98, 16, v48
	v_pk_add_f32 v[82:83], v[62:63], 0 op_sel_hi:[1,0]
	v_lshlrev_b32_e32 v87, 16, v47
	v_lshlrev_b32_e32 v86, 16, v46
	v_pk_fma_f32 v[90:91], v[64:65], v[84:85], v[88:89] op_sel_hi:[0,1,1] neg_lo:[0,0,1] neg_hi:[0,0,1]
	v_pk_add_f32 v[96:97], v[52:53], 0 op_sel_hi:[1,0]
	v_pk_add_f32 v[94:95], v[94:95], v[98:99]
	v_and_b32_e32 v101, 0xffff0000, v49
	v_and_b32_e32 v100, 0xffff0000, v48
	v_pk_add_f32 v[82:83], v[82:83], v[86:87]
	v_pk_add_f32 v[96:97], v[96:97], v[100:101]
	v_pk_fma_f32 v[48:49], v[64:65], v[94:95], v[98:99] op_sel_hi:[0,1,1] neg_lo:[0,0,1] neg_hi:[0,0,1]
	v_bfe_u32 v103, v90, 16, 1
	v_pk_fma_f32 v[46:47], v[64:65], v[82:83], v[86:87] op_sel_hi:[0,1,1] neg_lo:[0,0,1] neg_hi:[0,0,1]
	v_pk_fma_f32 v[64:65], v[64:65], v[96:97], v[100:101] op_sel_hi:[0,1,1] neg_lo:[0,0,1] neg_hi:[0,0,1]
	v_add3_u32 v90, v90, v103, s15
	v_bfe_u32 v103, v49, 16, 1
	v_bfe_u32 v55, v65, 16, 1
	v_add3_u32 v49, v49, v103, s15
	v_add3_u32 v55, v65, v55, s15
	v_lshrrev_b32_e32 v49, 16, v49
	v_bfe_u32 v61, v64, 16, 1
	v_and_or_b32 v49, v55, s90, v49
	v_ashrrev_i32_e32 v55, 4, v60
	v_add3_u32 v61, v64, v61, s15
	v_bfe_u32 v64, v46, 16, 1
	v_and_b32_e32 v55, -16, v55
	v_add3_u32 v46, v46, v64, s15
	v_add_u32_e32 v64, v55, v173
	v_lshlrev_b32_e32 v55, 6, v60
	v_min_u32_e32 v60, s28, v59
	v_sub_u32_e32 v2, v60, v2
	v_lshrrev_b32_e32 v46, 16, v46
	v_add_u32_e32 v2, 1, v2
	v_bfe_u32 v102, v91, 16, 1
	v_and_or_b32 v46, v90, s90, v46
	v_cvt_f32_i32_e32 v90, v2
	v_add3_u32 v91, v91, v102, s15
	v_bfe_u32 v102, v48, 16, 1
	v_bfe_u32 v65, v47, 16, 1
	v_add3_u32 v48, v48, v102, s15
	v_add3_u32 v47, v47, v65, s15
	v_lshrrev_b32_e32 v48, 16, v48
	v_ashrrev_i32_e32 v65, 31, v64
	v_and_or_b32 v48, v61, s90, v48
	v_lshlrev_b64 v[60:61], 15, v[64:65]
	v_div_scale_f32 v64, s[70:71], v90, v90, 1.0
	v_rcp_f32_e32 v65, v64
	v_and_or_b32 v55, v55, s63, v174
	v_lshl_add_u64 v[60:61], s[2:3], 0, v[60:61]
	v_lshlrev_b32_e32 v2, 1, v55
	v_lshrrev_b32_e32 v47, 16, v47
	v_lshl_add_u64 v[60:61], v[60:61], 0, v[2:3]
	v_fma_f32 v2, -v64, v65, 1.0
	v_and_or_b32 v47, v91, s90, v47
	v_fmac_f32_e32 v65, v2, v65
	v_div_scale_f32 v2, vcc, 1.0, v90, 1.0
	global_store_dwordx4 v[60:61], v[46:49], off sc1
	s_nop 1
	v_mul_f32_e32 v46, v2, v65
	v_fma_f32 v47, -v64, v46, v2
	v_fmac_f32_e32 v46, v47, v65
	v_fma_f32 v2, -v64, v46, v2
	v_div_fmas_f32 v2, v2, v65, v46
	v_lshlrev_b32_e32 v47, 16, v43
	v_lshlrev_b32_e32 v46, 16, v42
	v_and_b32_e32 v49, 0xffff0000, v43
	v_and_b32_e32 v48, 0xffff0000, v42
	v_pk_add_f32 v[42:43], v[82:83], v[62:63] neg_lo:[0,1] neg_hi:[0,1]
	v_div_fixup_f32 v2, v2, v90, 1.0
	v_pk_add_f32 v[60:61], v[42:43], v[46:47]
	v_pk_add_f32 v[42:43], v[84:85], v[50:51] neg_lo:[0,1] neg_hi:[0,1]
	v_lshlrev_b32_e32 v65, 16, v45
	v_pk_add_f32 v[50:51], v[42:43], v[48:49]
	v_lshlrev_b32_e32 v64, 16, v44
	v_and_b32_e32 v83, 0xffff0000, v45
	v_and_b32_e32 v82, 0xffff0000, v44
	v_pk_add_f32 v[44:45], v[94:95], v[92:93] neg_lo:[0,1] neg_hi:[0,1]
	v_pk_fma_f32 v[62:63], v[2:3], v[50:51], v[48:49] op_sel_hi:[0,1,1] neg_lo:[0,0,1] neg_hi:[0,0,1]
	v_pk_add_f32 v[84:85], v[44:45], v[64:65]
	v_pk_add_f32 v[44:45], v[96:97], v[52:53] neg_lo:[0,1] neg_hi:[0,1]
	v_bfe_u32 v92, v63, 16, 1
	v_pk_add_f32 v[52:53], v[44:45], v[82:83]
	v_pk_fma_f32 v[44:45], v[2:3], v[84:85], v[64:65] op_sel_hi:[0,1,1] neg_lo:[0,0,1] neg_hi:[0,0,1]
	v_pk_fma_f32 v[90:91], v[2:3], v[52:53], v[82:83] op_sel_hi:[0,1,1] neg_lo:[0,0,1] neg_hi:[0,0,1]
	v_add3_u32 v63, v63, v92, s15
	v_bfe_u32 v92, v44, 16, 1
	v_bfe_u32 v55, v90, 16, 1
	v_add3_u32 v44, v44, v92, s15
	v_bfe_u32 v93, v62, 16, 1
	v_add3_u32 v55, v90, v55, s15
	v_lshrrev_b32_e32 v44, 16, v44
	v_add3_u32 v62, v62, v93, s15
	v_bfe_u32 v93, v45, 16, 1
	v_and_or_b32 v44, v55, s90, v44
	v_min_u32_e32 v55, s28, v57
	v_pk_fma_f32 v[42:43], v[2:3], v[60:61], v[46:47] op_sel_hi:[0,1,1] neg_lo:[0,0,1] neg_hi:[0,0,1]
	v_bfe_u32 v2, v91, 16, 1
	v_add3_u32 v45, v45, v93, s15
	v_sub_u32_e32 v55, v55, v59
	v_add3_u32 v2, v91, v2, s15
	v_bfe_u32 v90, v42, 16, 1
	v_lshrrev_b32_e32 v45, 16, v45
	v_add_u32_e32 v55, 1, v55
	v_bfe_u32 v91, v43, 16, 1
	v_add3_u32 v42, v42, v90, s15
	v_and_or_b32 v45, v2, s90, v45
	v_ashrrev_i32_e32 v2, 4, v58
	v_cvt_f32_i32_e32 v55, v55
	v_add3_u32 v43, v43, v91, s15
	v_lshrrev_b32_e32 v42, 16, v42
	v_and_b32_e32 v2, -16, v2
	v_lshrrev_b32_e32 v43, 16, v43
	v_and_or_b32 v42, v62, s90, v42
	v_add_u32_e32 v62, v2, v173
	v_and_or_b32 v43, v63, s90, v43
	v_ashrrev_i32_e32 v63, 31, v62
	v_lshlrev_b32_e32 v2, 6, v58
; #define LDS_WAIT() asm volatile("s_waitcnt lgkmcnt(0)" ::: "memory")
; #define VM_WAIT() asm volatile("s_waitcnt vmcnt(0)" ::: "memory")
; __device__ __forceinline__ unsigned pk2(float lo, float hi) { return f2bf(lo) | (f2bf(hi) << 16); }
; __device__ __forceinline__ size_t blk_off(int row, int col, int K) { return ((size_t)((row >> 8) * (K >> 6) + (col >> 6)) << 14) + (size_t)(((row & 255) << 6) + (col & 63)); }
; #define POOL_ADD(sgn, VV) do { S[0] += sgn bflo((VV).x); S[1] += sgn bfhi((VV).x); S[2] += sgn bflo((VV).y); S[3] += sgn bfhi((VV).y); S[4] += sgn bflo((VV).z); S[5] += sgn bfhi((VV).z); S[6] += sgn bflo((VV).w); S[7] += sgn bfhi((VV).w); } while (0)
; template <int HW> __device__ __forceinline__ void pool_group(const bf16* PROJ, bf16* CAT, int pbase, int T, int t0, int ch) {
;     ...
;     for (int k = 0; k < 4; ++k) {
;         if (k > 0) { POOL_ADD(-, x[k - 1]); POOL_ADD(+, x[k - 1 + 2 * HW]); }
;         const int t = t0 + k; const float ic = 1.0f / (float)(min(t + HW, T) - max(t - HW, 0)); const v4u w = x[HW + k];
;         v4u ow; ow.x = pk2(S[0] * ic - bflo(w.x), S[1] * ic - bfhi(w.x)); ow.y = pk2(S[2] * ic - bflo(w.y), S[3] * ic - bfhi(w.y));
;         ow.z = pk2(S[4] * ic - bflo(w.z), S[5] * ic - bfhi(w.z)); ow.w = pk2(S[6] * ic - bflo(w.w), S[7] * ic - bfhi(w.w));
;         *(v4u*)(CAT + blk_off(pbase + t, ATTW + 8 * ch, D)) = ow;
; __global__ void __launch_bounds__(NWAVES * 64, 2) fwd(Args a) {
;     ...
;             for (int st = 0; st < 16; ++st) {
;                 if (wave < 4 && st > 0) asm volatile("s_waitcnt vmcnt(2)" ::: "memory"); else VM_WAIT();
;                 LDS_WAIT(); __builtin_amdgcn_s_barrier(); asm volatile("" ::: "memory");
	v_lshlrev_b64 v[58:59], 15, v[62:63]
	v_div_scale_f32 v62, s[70:71], v55, v55, 1.0
	v_rcp_f32_e32 v63, v62
	v_and_or_b32 v2, v2, s63, v174
	v_lshl_add_u64 v[58:59], s[2:3], 0, v[58:59]
	v_lshlrev_b32_e32 v2, 1, v2
	v_lshl_add_u64 v[58:59], v[58:59], 0, v[2:3]
	v_fma_f32 v2, -v62, v63, 1.0
	v_fmac_f32_e32 v63, v2, v63
	v_div_scale_f32 v2, vcc, 1.0, v55, 1.0
	global_store_dwordx4 v[58:59], v[42:45], off sc1
	v_pk_add_f32 v[50:51], v[50:51], v[88:89] neg_lo:[0,1] neg_hi:[0,1]
	v_pk_add_f32 v[58:59], v[84:85], v[98:99] neg_lo:[0,1] neg_hi:[0,1]
	v_mul_f32_e32 v42, v2, v63
	v_fma_f32 v43, -v62, v42, v2
	v_fmac_f32_e32 v42, v43, v63
	v_fma_f32 v2, -v62, v42, v2
	v_div_fmas_f32 v2, v2, v63, v42
	v_lshlrev_b32_e32 v45, 16, v39
	v_lshlrev_b32_e32 v44, 16, v38
	v_and_b32_e32 v39, 0xffff0000, v39
	v_and_b32_e32 v38, 0xffff0000, v38
	v_div_fixup_f32 v2, v2, v55, 1.0
	v_pk_add_f32 v[42:43], v[60:61], v[86:87] neg_lo:[0,1] neg_hi:[0,1]
	v_pk_add_f32 v[50:51], v[50:51], v[38:39]
	v_lshlrev_b32_e32 v61, 16, v41
	v_lshlrev_b32_e32 v60, 16, v40
	v_pk_add_f32 v[52:53], v[52:53], v[100:101] neg_lo:[0,1] neg_hi:[0,1]
	v_and_b32_e32 v41, 0xffff0000, v41
	v_and_b32_e32 v40, 0xffff0000, v40
	v_pk_fma_f32 v[38:39], v[2:3], v[50:51], v[38:39] op_sel_hi:[0,1,1] neg_lo:[0,0,1] neg_hi:[0,0,1]
	v_pk_add_f32 v[58:59], v[58:59], v[60:61]
	v_pk_add_f32 v[52:53], v[52:53], v[40:41]
	v_pk_add_f32 v[42:43], v[42:43], v[44:45]
	v_pk_fma_f32 v[60:61], v[2:3], v[58:59], v[60:61] op_sel_hi:[0,1,1] neg_lo:[0,0,1] neg_hi:[0,0,1]
	v_pk_fma_f32 v[40:41], v[2:3], v[52:53], v[40:41] op_sel_hi:[0,1,1] neg_lo:[0,0,1] neg_hi:[0,0,1]
	v_bfe_u32 v62, v39, 16, 1
	v_pk_fma_f32 v[44:45], v[2:3], v[42:43], v[44:45] op_sel_hi:[0,1,1] neg_lo:[0,0,1] neg_hi:[0,0,1]
	v_bfe_u32 v55, v40, 16, 1
	v_add3_u32 v39, v39, v62, s15
	v_bfe_u32 v62, v60, 16, 1
	v_add3_u32 v40, v40, v55, s15
	v_bfe_u32 v55, v45, 16, 1
	v_add3_u32 v60, v60, v62, s15
	v_add3_u32 v45, v45, v55, s15
	v_lshrrev_b32_e32 v55, 16, v60
	v_and_or_b32 v40, v40, s90, v55
	v_add_u32_e32 v55, 4, v196
	v_min_u32_e32 v55, s28, v55
	v_bfe_u32 v2, v41, 16, 1
	v_bfe_u32 v63, v38, 16, 1
	v_sub_u32_e32 v55, v55, v57
	v_add3_u32 v38, v38, v63, s15
	v_add3_u32 v2, v41, v2, s15
	v_bfe_u32 v41, v44, 16, 1
	v_bfe_u32 v63, v61, 16, 1
	v_add_u32_e32 v55, 1, v55
	v_add3_u32 v61, v61, v63, s15
	v_add3_u32 v41, v44, v41, s15
	v_cvt_f32_i32_e32 v55, v55
	v_lshrrev_b32_e32 v44, 16, v41
	v_lshrrev_b32_e32 v41, 16, v61
	v_and_or_b32 v41, v2, s90, v41
	v_ashrrev_i32_e32 v2, 4, v56
	v_and_b32_e32 v2, -16, v2
	v_and_or_b32 v38, v38, s90, v44
	v_add_u32_e32 v44, v2, v173
	v_lshlrev_b32_e32 v2, 6, v56
	v_div_scale_f32 v56, s[70:71], v55, v55, 1.0
	v_lshrrev_b32_e32 v45, 16, v45
	v_rcp_f32_e32 v57, v56
	v_and_or_b32 v39, v39, s90, v45
	v_ashrrev_i32_e32 v45, 31, v44
	v_and_or_b32 v2, v2, s63, v174
	v_lshlrev_b64 v[44:45], 15, v[44:45]
	v_lshl_add_u64 v[44:45], s[2:3], 0, v[44:45]
	v_lshlrev_b32_e32 v2, 1, v2
	v_lshl_add_u64 v[44:45], v[44:45], 0, v[2:3]
	v_fma_f32 v2, -v56, v57, 1.0
	v_fmac_f32_e32 v57, v2, v57
	v_div_scale_f32 v2, vcc, 1.0, v55, 1.0
	global_store_dwordx4 v[44:45], v[38:41], off sc1
	v_pk_add_f32 v[44:45], v[52:53], v[82:83] neg_lo:[0,1] neg_hi:[0,1]
	s_nop 0
	v_mul_f32_e32 v38, v2, v57
	v_fma_f32 v39, -v56, v38, v2
	v_fmac_f32_e32 v38, v39, v57
	v_fma_f32 v2, -v56, v38, v2
	v_div_fmas_f32 v2, v2, v57, v38
	v_pk_add_f32 v[38:39], v[42:43], v[46:47] neg_lo:[0,1] neg_hi:[0,1]
	v_lshlrev_b32_e32 v41, 16, v35
	v_lshlrev_b32_e32 v40, 16, v34
	v_pk_add_f32 v[42:43], v[50:51], v[48:49] neg_lo:[0,1] neg_hi:[0,1]
	v_and_b32_e32 v35, 0xffff0000, v35
	v_and_b32_e32 v34, 0xffff0000, v34
	v_div_fixup_f32 v2, v2, v55, 1.0
	v_pk_add_f32 v[42:43], v[42:43], v[34:35]
	v_pk_add_f32 v[38:39], v[38:39], v[40:41]
	v_pk_fma_f32 v[34:35], v[2:3], v[42:43], v[34:35] op_sel_hi:[0,1,1] neg_lo:[0,0,1] neg_hi:[0,0,1]
	v_lshlrev_b32_e32 v43, 16, v37
	v_lshlrev_b32_e32 v42, 16, v36
	v_and_b32_e32 v37, 0xffff0000, v37
	v_and_b32_e32 v36, 0xffff0000, v36
	v_pk_fma_f32 v[38:39], v[2:3], v[38:39], v[40:41] op_sel_hi:[0,1,1] neg_lo:[0,0,1] neg_hi:[0,0,1]
	v_pk_add_f32 v[40:41], v[58:59], v[64:65] neg_lo:[0,1] neg_hi:[0,1]
	v_pk_add_f32 v[44:45], v[44:45], v[36:37]
	v_pk_add_f32 v[40:41], v[40:41], v[42:43]
	v_pk_fma_f32 v[36:37], v[2:3], v[44:45], v[36:37] op_sel_hi:[0,1,1] neg_lo:[0,0,1] neg_hi:[0,0,1]
	v_pk_fma_f32 v[40:41], v[2:3], v[40:41], v[42:43] op_sel_hi:[0,1,1] neg_lo:[0,0,1] neg_hi:[0,0,1]
	v_bfe_u32 v2, v37, 16, 1
	v_bfe_u32 v44, v34, 16, 1
	v_add3_u32 v34, v34, v44, s15
	v_add3_u32 v2, v37, v2, s15
	v_bfe_u32 v37, v38, 16, 1
	v_bfe_u32 v44, v41, 16, 1
	v_add3_u32 v41, v41, v44, s15
	v_add3_u32 v37, v38, v37, s15
	v_bfe_u32 v42, v36, 16, 1
	v_lshrrev_b32_e32 v38, 16, v37
	v_lshrrev_b32_e32 v37, 16, v41
	v_add3_u32 v36, v36, v42, s15
	v_bfe_u32 v42, v39, 16, 1
	v_and_or_b32 v37, v2, s90, v37
	v_ashrrev_i32_e32 v2, 4, v54
	v_bfe_u32 v43, v35, 16, 1
	v_add3_u32 v39, v39, v42, s15
	v_and_b32_e32 v2, -16, v2
	v_add3_u32 v35, v35, v43, s15
	v_lshrrev_b32_e32 v39, 16, v39
	v_and_or_b32 v34, v34, s90, v38
	v_add_u32_e32 v38, v2, v173
	v_bfe_u32 v43, v40, 16, 1
	v_and_or_b32 v35, v35, s90, v39
	v_ashrrev_i32_e32 v39, 31, v38
	v_lshlrev_b32_e32 v2, 6, v54
	v_add3_u32 v40, v40, v43, s15
	v_and_or_b32 v2, v2, s63, v174
	v_lshlrev_b64 v[38:39], 15, v[38:39]
	v_lshrrev_b32_e32 v40, 16, v40
	v_lshl_add_u64 v[38:39], s[2:3], 0, v[38:39]
	v_lshlrev_b32_e32 v2, 1, v2
	v_and_or_b32 v36, v36, s90, v40
	v_lshl_add_u64 v[38:39], v[38:39], 0, v[2:3]
	global_store_dwordx4 v[38:39], v[34:37], off sc1
	s_cbranch_execnz .LBB0_261
	s_branch .LBB0_358
